# adds: HG in-proj activation epilogue regenerated (tile-uniform mode dispatch, lower-bound loads issued together, 128-byte store pieces)
# speedup vs baseline: 1.0452x; 1.0078x over previous
.LBB0_274:
	s_ashr_i32 s23, s34, 2
	s_lshl_b32 s86, s35, 11
	s_add_i32 s86, s86, 0x20400
	s_lshl_b32 s87, s4, 2
	s_add_i32 s87, s86, s87
	v_lshl_add_u32 v172, v209, 2, s87
	ds_read_b32 v176, v172 offset:0
	ds_read_b32 v177, v172 offset:64
	ds_read_b32 v178, v172 offset:128
	ds_read_b32 v180, v172 offset:192
	ds_read_b32 v181, v172 offset:512
	ds_read_b32 v182, v172 offset:576
	ds_read_b32 v188, v172 offset:640
	ds_read_b32 v189, v172 offset:704
	s_lshl_b32 s87, s43, 2
	s_add_i32 s87, s86, s87
	v_lshl_add_u32 v172, v211, 2, s87
	ds_read_b128 v[26:29], v172 offset:1024
	ds_read_b128 v[30:33], v172 offset:1040
	ds_read_b128 v[42:45], v172 offset:1536
	ds_read_b128 v[46:49], v172 offset:1552
	s_mov_b32 s62, 0xaaaaaaaa
	s_mov_b32 s63, 0xaaaaaaaa
	s_mov_b32 s84, 0x55555555
	s_mov_b32 s85, 0x55555555
	v_and_b32_e32 v174, 1, v209
	v_lshl_or_b32 v215, s43, 1, v211
	v_lshl_or_b32 v215, s34, 8, v215
	v_lshl_add_u32 v173, v174, 5, v215
	v_lshl_add_u32 v172, s48, 8, v210
	v_sub_u32_e32 v172, v172, v174
	v_lshlrev_b32_e32 v172, 13, v172
	v_lshl_add_u32 v173, v173, 1, v172
	s_cmp_eq_u32 s23, 1
	s_cbranch_scc1 .Lact1_hgin_kk
	s_cmp_eq_u32 s23, 2
	s_cbranch_scc1 .Lact1_hgin_id
	s_waitcnt lgkmcnt(0)
	v_fma_f32 v142, v142, v176, v26
	v_fma_f32 v143, v143, v176, v27
	v_fma_f32 v144, v144, v176, v28
	v_fma_f32 v145, v145, v176, v29
	v_fma_f32 v138, v138, v176, v30
	v_fma_f32 v139, v139, v176, v31
	v_fma_f32 v140, v140, v176, v32
	v_fma_f32 v141, v141, v176, v33
	v_mul_f32_e32 v216, 0xbfb8aa3b, v142
	v_mul_f32_e32 v217, 0xbfb8aa3b, v143
	v_mul_f32_e32 v218, 0xbfb8aa3b, v144
	v_mul_f32_e32 v219, 0xbfb8aa3b, v145
	v_mul_f32_e32 v220, 0xbfb8aa3b, v138
	v_mul_f32_e32 v221, 0xbfb8aa3b, v139
	v_mul_f32_e32 v222, 0xbfb8aa3b, v140
	v_mul_f32_e32 v223, 0xbfb8aa3b, v141
	v_exp_f32_e32 v216, v216
	v_exp_f32_e32 v217, v217
	v_exp_f32_e32 v218, v218
	v_exp_f32_e32 v219, v219
	v_exp_f32_e32 v220, v220
	v_exp_f32_e32 v221, v221
	v_exp_f32_e32 v222, v222
	v_exp_f32_e32 v223, v223
	v_add_f32_e32 v216, 1.0, v216
	v_add_f32_e32 v217, 1.0, v217
	v_add_f32_e32 v218, 1.0, v218
	v_add_f32_e32 v219, 1.0, v219
	v_add_f32_e32 v220, 1.0, v220
	v_add_f32_e32 v221, 1.0, v221
	v_add_f32_e32 v222, 1.0, v222
	v_add_f32_e32 v223, 1.0, v223
	v_rcp_f32_e32 v216, v216
	v_rcp_f32_e32 v217, v217
	v_rcp_f32_e32 v218, v218
	v_rcp_f32_e32 v219, v219
	v_rcp_f32_e32 v220, v220
	v_rcp_f32_e32 v221, v221
	v_rcp_f32_e32 v222, v222
	v_rcp_f32_e32 v223, v223
	v_pk_mul_f32 v[142:143], v[142:143], v[216:217]
	v_pk_mul_f32 v[144:145], v[144:145], v[218:219]
	v_pk_mul_f32 v[138:139], v[138:139], v[220:221]
	v_pk_mul_f32 v[140:141], v[140:141], v[222:223]
	v_cvt_pk_bf16_f32 v168, v142, v143
	v_cvt_pk_bf16_f32 v169, v144, v145
	v_cvt_pk_bf16_f32 v170, v138, v139
	v_cvt_pk_bf16_f32 v171, v140, v141
	v_fma_f32 v134, v134, v176, v42
	v_fma_f32 v135, v135, v176, v43
	v_fma_f32 v136, v136, v176, v44
	v_fma_f32 v137, v137, v176, v45
	v_fma_f32 v130, v130, v176, v46
	v_fma_f32 v131, v131, v176, v47
	v_fma_f32 v132, v132, v176, v48
	v_fma_f32 v133, v133, v176, v49
	v_mul_f32_e32 v216, 0xbfb8aa3b, v134
	v_mul_f32_e32 v217, 0xbfb8aa3b, v135
	v_mul_f32_e32 v218, 0xbfb8aa3b, v136
	v_mul_f32_e32 v219, 0xbfb8aa3b, v137
	v_mul_f32_e32 v220, 0xbfb8aa3b, v130
	v_mul_f32_e32 v221, 0xbfb8aa3b, v131
	v_mul_f32_e32 v222, 0xbfb8aa3b, v132
	v_mul_f32_e32 v223, 0xbfb8aa3b, v133
	v_exp_f32_e32 v216, v216
	v_exp_f32_e32 v217, v217
	v_exp_f32_e32 v218, v218
	v_exp_f32_e32 v219, v219
	v_exp_f32_e32 v220, v220
	v_exp_f32_e32 v221, v221
	v_exp_f32_e32 v222, v222
	v_exp_f32_e32 v223, v223
	v_add_f32_e32 v216, 1.0, v216
	v_add_f32_e32 v217, 1.0, v217
	v_add_f32_e32 v218, 1.0, v218
	v_add_f32_e32 v219, 1.0, v219
	v_add_f32_e32 v220, 1.0, v220
	v_add_f32_e32 v221, 1.0, v221
	v_add_f32_e32 v222, 1.0, v222
	v_add_f32_e32 v223, 1.0, v223
	v_rcp_f32_e32 v216, v216
	v_rcp_f32_e32 v217, v217
	v_rcp_f32_e32 v218, v218
	v_rcp_f32_e32 v219, v219
	v_rcp_f32_e32 v220, v220
	v_rcp_f32_e32 v221, v221
	v_rcp_f32_e32 v222, v222
	v_rcp_f32_e32 v223, v223
	v_pk_mul_f32 v[134:135], v[134:135], v[216:217]
	v_pk_mul_f32 v[136:137], v[136:137], v[218:219]
	v_pk_mul_f32 v[130:131], v[130:131], v[220:221]
	v_pk_mul_f32 v[132:133], v[132:133], v[222:223]
	v_cvt_pk_bf16_f32 v184, v134, v135
	v_cvt_pk_bf16_f32 v185, v136, v137
	v_cvt_pk_bf16_f32 v186, v130, v131
	v_cvt_pk_bf16_f32 v187, v132, v133
	v_mov_b32_dpp v216, v168 quad_perm:[1,0,3,2] row_mask:0xf bank_mask:0xf
	v_mov_b32_dpp v217, v169 quad_perm:[1,0,3,2] row_mask:0xf bank_mask:0xf
	v_mov_b32_dpp v218, v170 quad_perm:[1,0,3,2] row_mask:0xf bank_mask:0xf
	v_mov_b32_dpp v219, v171 quad_perm:[1,0,3,2] row_mask:0xf bank_mask:0xf
	v_mov_b32_dpp v220, v184 quad_perm:[1,0,3,2] row_mask:0xf bank_mask:0xf
	v_mov_b32_dpp v221, v185 quad_perm:[1,0,3,2] row_mask:0xf bank_mask:0xf
	v_mov_b32_dpp v222, v186 quad_perm:[1,0,3,2] row_mask:0xf bank_mask:0xf
	v_mov_b32_dpp v223, v187 quad_perm:[1,0,3,2] row_mask:0xf bank_mask:0xf
	s_mov_b64 exec, s[62:63]
	v_mov_b32_e32 v168, v220
	v_mov_b32_e32 v169, v221
	v_mov_b32_e32 v170, v222
	v_mov_b32_e32 v171, v223
	s_mov_b64 exec, s[84:85]
	v_mov_b32_e32 v184, v216
	v_mov_b32_e32 v185, v217
	v_mov_b32_e32 v186, v218
	v_mov_b32_e32 v187, v219
	s_mov_b64 exec, -1
	s_add_u32 s80, s10, 0x0
	s_addc_u32 s81, s11, 0
	s_add_u32 s82, s10, 0x2000
	s_addc_u32 s83, s11, 0
	global_store_dwordx4 v173, v[168:171], s[80:81]
	global_store_dwordx4 v173, v[184:187], s[82:83]
	v_fma_f32 v126, v126, v177, v26
	v_fma_f32 v127, v127, v177, v27
	v_fma_f32 v128, v128, v177, v28
	v_fma_f32 v129, v129, v177, v29
	v_fma_f32 v122, v122, v177, v30
	v_fma_f32 v123, v123, v177, v31
	v_fma_f32 v124, v124, v177, v32
	v_fma_f32 v125, v125, v177, v33
	v_mul_f32_e32 v216, 0xbfb8aa3b, v126
	v_mul_f32_e32 v217, 0xbfb8aa3b, v127
	v_mul_f32_e32 v218, 0xbfb8aa3b, v128
	v_mul_f32_e32 v219, 0xbfb8aa3b, v129
	v_mul_f32_e32 v220, 0xbfb8aa3b, v122
	v_mul_f32_e32 v221, 0xbfb8aa3b, v123
	v_mul_f32_e32 v222, 0xbfb8aa3b, v124
	v_mul_f32_e32 v223, 0xbfb8aa3b, v125
	v_exp_f32_e32 v216, v216
	v_exp_f32_e32 v217, v217
	v_exp_f32_e32 v218, v218
	v_exp_f32_e32 v219, v219
	v_exp_f32_e32 v220, v220
	v_exp_f32_e32 v221, v221
	v_exp_f32_e32 v222, v222
	v_exp_f32_e32 v223, v223
	v_add_f32_e32 v216, 1.0, v216
	v_add_f32_e32 v217, 1.0, v217
	v_add_f32_e32 v218, 1.0, v218
	v_add_f32_e32 v219, 1.0, v219
	v_add_f32_e32 v220, 1.0, v220
	v_add_f32_e32 v221, 1.0, v221
	v_add_f32_e32 v222, 1.0, v222
	v_add_f32_e32 v223, 1.0, v223
	v_rcp_f32_e32 v216, v216
	v_rcp_f32_e32 v217, v217
	v_rcp_f32_e32 v218, v218
	v_rcp_f32_e32 v219, v219
	v_rcp_f32_e32 v220, v220
	v_rcp_f32_e32 v221, v221
	v_rcp_f32_e32 v222, v222
	v_rcp_f32_e32 v223, v223
	v_pk_mul_f32 v[126:127], v[126:127], v[216:217]
	v_pk_mul_f32 v[128:129], v[128:129], v[218:219]
	v_pk_mul_f32 v[122:123], v[122:123], v[220:221]
	v_pk_mul_f32 v[124:125], v[124:125], v[222:223]
	v_cvt_pk_bf16_f32 v168, v126, v127
	v_cvt_pk_bf16_f32 v169, v128, v129
	v_cvt_pk_bf16_f32 v170, v122, v123
	v_cvt_pk_bf16_f32 v171, v124, v125
	v_fma_f32 v118, v118, v177, v42
	v_fma_f32 v119, v119, v177, v43
	v_fma_f32 v120, v120, v177, v44
	v_fma_f32 v121, v121, v177, v45
	v_fma_f32 v114, v114, v177, v46
	v_fma_f32 v115, v115, v177, v47
	v_fma_f32 v116, v116, v177, v48
	v_fma_f32 v117, v117, v177, v49
	v_mul_f32_e32 v216, 0xbfb8aa3b, v118
	v_mul_f32_e32 v217, 0xbfb8aa3b, v119
	v_mul_f32_e32 v218, 0xbfb8aa3b, v120
	v_mul_f32_e32 v219, 0xbfb8aa3b, v121
	v_mul_f32_e32 v220, 0xbfb8aa3b, v114
	v_mul_f32_e32 v221, 0xbfb8aa3b, v115
	v_mul_f32_e32 v222, 0xbfb8aa3b, v116
	v_mul_f32_e32 v223, 0xbfb8aa3b, v117
	v_exp_f32_e32 v216, v216
	v_exp_f32_e32 v217, v217
	v_exp_f32_e32 v218, v218
	v_exp_f32_e32 v219, v219
	v_exp_f32_e32 v220, v220
	v_exp_f32_e32 v221, v221
	v_exp_f32_e32 v222, v222
	v_exp_f32_e32 v223, v223
	v_add_f32_e32 v216, 1.0, v216
	v_add_f32_e32 v217, 1.0, v217
	v_add_f32_e32 v218, 1.0, v218
	v_add_f32_e32 v219, 1.0, v219
	v_add_f32_e32 v220, 1.0, v220
	v_add_f32_e32 v221, 1.0, v221
	v_add_f32_e32 v222, 1.0, v222
	v_add_f32_e32 v223, 1.0, v223
	v_rcp_f32_e32 v216, v216
	v_rcp_f32_e32 v217, v217
	v_rcp_f32_e32 v218, v218
	v_rcp_f32_e32 v219, v219
	v_rcp_f32_e32 v220, v220
	v_rcp_f32_e32 v221, v221
	v_rcp_f32_e32 v222, v222
	v_rcp_f32_e32 v223, v223
	v_pk_mul_f32 v[118:119], v[118:119], v[216:217]
	v_pk_mul_f32 v[120:121], v[120:121], v[218:219]
	v_pk_mul_f32 v[114:115], v[114:115], v[220:221]
	v_pk_mul_f32 v[116:117], v[116:117], v[222:223]
	v_cvt_pk_bf16_f32 v184, v118, v119
	v_cvt_pk_bf16_f32 v185, v120, v121
	v_cvt_pk_bf16_f32 v186, v114, v115
	v_cvt_pk_bf16_f32 v187, v116, v117
	v_mov_b32_dpp v216, v168 quad_perm:[1,0,3,2] row_mask:0xf bank_mask:0xf
	v_mov_b32_dpp v217, v169 quad_perm:[1,0,3,2] row_mask:0xf bank_mask:0xf
	v_mov_b32_dpp v218, v170 quad_perm:[1,0,3,2] row_mask:0xf bank_mask:0xf
	v_mov_b32_dpp v219, v171 quad_perm:[1,0,3,2] row_mask:0xf bank_mask:0xf
	v_mov_b32_dpp v220, v184 quad_perm:[1,0,3,2] row_mask:0xf bank_mask:0xf
	v_mov_b32_dpp v221, v185 quad_perm:[1,0,3,2] row_mask:0xf bank_mask:0xf
	v_mov_b32_dpp v222, v186 quad_perm:[1,0,3,2] row_mask:0xf bank_mask:0xf
	v_mov_b32_dpp v223, v187 quad_perm:[1,0,3,2] row_mask:0xf bank_mask:0xf
	s_mov_b64 exec, s[62:63]
	v_mov_b32_e32 v168, v220
	v_mov_b32_e32 v169, v221
	v_mov_b32_e32 v170, v222
	v_mov_b32_e32 v171, v223
	s_mov_b64 exec, s[84:85]
	v_mov_b32_e32 v184, v216
	v_mov_b32_e32 v185, v217
	v_mov_b32_e32 v186, v218
	v_mov_b32_e32 v187, v219
	s_mov_b64 exec, -1
	s_add_u32 s80, s10, 0x20000
	s_addc_u32 s81, s11, 0
	s_add_u32 s82, s10, 0x22000
	s_addc_u32 s83, s11, 0
	global_store_dwordx4 v173, v[168:171], s[80:81]
	global_store_dwordx4 v173, v[184:187], s[82:83]
	v_fma_f32 v110, v110, v178, v26
	v_fma_f32 v111, v111, v178, v27
	v_fma_f32 v112, v112, v178, v28
	v_fma_f32 v113, v113, v178, v29
	v_fma_f32 v106, v106, v178, v30
	v_fma_f32 v107, v107, v178, v31
	v_fma_f32 v108, v108, v178, v32
	v_fma_f32 v109, v109, v178, v33
	v_mul_f32_e32 v216, 0xbfb8aa3b, v110
	v_mul_f32_e32 v217, 0xbfb8aa3b, v111
	v_mul_f32_e32 v218, 0xbfb8aa3b, v112
	v_mul_f32_e32 v219, 0xbfb8aa3b, v113
	v_mul_f32_e32 v220, 0xbfb8aa3b, v106
	v_mul_f32_e32 v221, 0xbfb8aa3b, v107
	v_mul_f32_e32 v222, 0xbfb8aa3b, v108
	v_mul_f32_e32 v223, 0xbfb8aa3b, v109
	v_exp_f32_e32 v216, v216
	v_exp_f32_e32 v217, v217
	v_exp_f32_e32 v218, v218
	v_exp_f32_e32 v219, v219
	v_exp_f32_e32 v220, v220
	v_exp_f32_e32 v221, v221
	v_exp_f32_e32 v222, v222
	v_exp_f32_e32 v223, v223
	v_add_f32_e32 v216, 1.0, v216
	v_add_f32_e32 v217, 1.0, v217
	v_add_f32_e32 v218, 1.0, v218
	v_add_f32_e32 v219, 1.0, v219
	v_add_f32_e32 v220, 1.0, v220
	v_add_f32_e32 v221, 1.0, v221
	v_add_f32_e32 v222, 1.0, v222
	v_add_f32_e32 v223, 1.0, v223
	v_rcp_f32_e32 v216, v216
	v_rcp_f32_e32 v217, v217
	v_rcp_f32_e32 v218, v218
	v_rcp_f32_e32 v219, v219
	v_rcp_f32_e32 v220, v220
	v_rcp_f32_e32 v221, v221
	v_rcp_f32_e32 v222, v222
	v_rcp_f32_e32 v223, v223
	v_pk_mul_f32 v[110:111], v[110:111], v[216:217]
	v_pk_mul_f32 v[112:113], v[112:113], v[218:219]
	v_pk_mul_f32 v[106:107], v[106:107], v[220:221]
	v_pk_mul_f32 v[108:109], v[108:109], v[222:223]
	v_cvt_pk_bf16_f32 v168, v110, v111
	v_cvt_pk_bf16_f32 v169, v112, v113
	v_cvt_pk_bf16_f32 v170, v106, v107
	v_cvt_pk_bf16_f32 v171, v108, v109
	v_fma_f32 v102, v102, v178, v42
	v_fma_f32 v103, v103, v178, v43
	v_fma_f32 v104, v104, v178, v44
	v_fma_f32 v105, v105, v178, v45
	v_fma_f32 v98, v98, v178, v46
	v_fma_f32 v99, v99, v178, v47
	v_fma_f32 v100, v100, v178, v48
	v_fma_f32 v101, v101, v178, v49
	v_mul_f32_e32 v216, 0xbfb8aa3b, v102
	v_mul_f32_e32 v217, 0xbfb8aa3b, v103
	v_mul_f32_e32 v218, 0xbfb8aa3b, v104
	v_mul_f32_e32 v219, 0xbfb8aa3b, v105
	v_mul_f32_e32 v220, 0xbfb8aa3b, v98
	v_mul_f32_e32 v221, 0xbfb8aa3b, v99
	v_mul_f32_e32 v222, 0xbfb8aa3b, v100
	v_mul_f32_e32 v223, 0xbfb8aa3b, v101
	v_exp_f32_e32 v216, v216
	v_exp_f32_e32 v217, v217
	v_exp_f32_e32 v218, v218
	v_exp_f32_e32 v219, v219
	v_exp_f32_e32 v220, v220
	v_exp_f32_e32 v221, v221
	v_exp_f32_e32 v222, v222
	v_exp_f32_e32 v223, v223
	v_add_f32_e32 v216, 1.0, v216
	v_add_f32_e32 v217, 1.0, v217
	v_add_f32_e32 v218, 1.0, v218
	v_add_f32_e32 v219, 1.0, v219
	v_add_f32_e32 v220, 1.0, v220
	v_add_f32_e32 v221, 1.0, v221
	v_add_f32_e32 v222, 1.0, v222
	v_add_f32_e32 v223, 1.0, v223
	v_rcp_f32_e32 v216, v216
	v_rcp_f32_e32 v217, v217
	v_rcp_f32_e32 v218, v218
	v_rcp_f32_e32 v219, v219
	v_rcp_f32_e32 v220, v220
	v_rcp_f32_e32 v221, v221
	v_rcp_f32_e32 v222, v222
	v_rcp_f32_e32 v223, v223
	v_pk_mul_f32 v[102:103], v[102:103], v[216:217]
	v_pk_mul_f32 v[104:105], v[104:105], v[218:219]
	v_pk_mul_f32 v[98:99], v[98:99], v[220:221]
	v_pk_mul_f32 v[100:101], v[100:101], v[222:223]
	v_cvt_pk_bf16_f32 v184, v102, v103
	v_cvt_pk_bf16_f32 v185, v104, v105
	v_cvt_pk_bf16_f32 v186, v98, v99
	v_cvt_pk_bf16_f32 v187, v100, v101
	v_mov_b32_dpp v216, v168 quad_perm:[1,0,3,2] row_mask:0xf bank_mask:0xf
	v_mov_b32_dpp v217, v169 quad_perm:[1,0,3,2] row_mask:0xf bank_mask:0xf
	v_mov_b32_dpp v218, v170 quad_perm:[1,0,3,2] row_mask:0xf bank_mask:0xf
	v_mov_b32_dpp v219, v171 quad_perm:[1,0,3,2] row_mask:0xf bank_mask:0xf
	v_mov_b32_dpp v220, v184 quad_perm:[1,0,3,2] row_mask:0xf bank_mask:0xf
	v_mov_b32_dpp v221, v185 quad_perm:[1,0,3,2] row_mask:0xf bank_mask:0xf
	v_mov_b32_dpp v222, v186 quad_perm:[1,0,3,2] row_mask:0xf bank_mask:0xf
	v_mov_b32_dpp v223, v187 quad_perm:[1,0,3,2] row_mask:0xf bank_mask:0xf
	s_mov_b64 exec, s[62:63]
	v_mov_b32_e32 v168, v220
	v_mov_b32_e32 v169, v221
	v_mov_b32_e32 v170, v222
	v_mov_b32_e32 v171, v223
	s_mov_b64 exec, s[84:85]
	v_mov_b32_e32 v184, v216
	v_mov_b32_e32 v185, v217
	v_mov_b32_e32 v186, v218
	v_mov_b32_e32 v187, v219
	s_mov_b64 exec, -1
	s_add_u32 s80, s10, 0x40000
	s_addc_u32 s81, s11, 0
	s_add_u32 s82, s10, 0x42000
	s_addc_u32 s83, s11, 0
	global_store_dwordx4 v173, v[168:171], s[80:81]
	global_store_dwordx4 v173, v[184:187], s[82:83]
	v_fma_f32 v94, v94, v180, v26
	v_fma_f32 v95, v95, v180, v27
	v_fma_f32 v96, v96, v180, v28
	v_fma_f32 v97, v97, v180, v29
	v_fma_f32 v90, v90, v180, v30
	v_fma_f32 v91, v91, v180, v31
	v_fma_f32 v92, v92, v180, v32
	v_fma_f32 v93, v93, v180, v33
	v_mul_f32_e32 v216, 0xbfb8aa3b, v94
	v_mul_f32_e32 v217, 0xbfb8aa3b, v95
	v_mul_f32_e32 v218, 0xbfb8aa3b, v96
	v_mul_f32_e32 v219, 0xbfb8aa3b, v97
	v_mul_f32_e32 v220, 0xbfb8aa3b, v90
	v_mul_f32_e32 v221, 0xbfb8aa3b, v91
	v_mul_f32_e32 v222, 0xbfb8aa3b, v92
	v_mul_f32_e32 v223, 0xbfb8aa3b, v93
	v_exp_f32_e32 v216, v216
	v_exp_f32_e32 v217, v217
	v_exp_f32_e32 v218, v218
	v_exp_f32_e32 v219, v219
	v_exp_f32_e32 v220, v220
	v_exp_f32_e32 v221, v221
	v_exp_f32_e32 v222, v222
	v_exp_f32_e32 v223, v223
	v_add_f32_e32 v216, 1.0, v216
	v_add_f32_e32 v217, 1.0, v217
	v_add_f32_e32 v218, 1.0, v218
	v_add_f32_e32 v219, 1.0, v219
	v_add_f32_e32 v220, 1.0, v220
	v_add_f32_e32 v221, 1.0, v221
	v_add_f32_e32 v222, 1.0, v222
	v_add_f32_e32 v223, 1.0, v223
	v_rcp_f32_e32 v216, v216
	v_rcp_f32_e32 v217, v217
	v_rcp_f32_e32 v218, v218
	v_rcp_f32_e32 v219, v219
	v_rcp_f32_e32 v220, v220
	v_rcp_f32_e32 v221, v221
	v_rcp_f32_e32 v222, v222
	v_rcp_f32_e32 v223, v223
	v_pk_mul_f32 v[94:95], v[94:95], v[216:217]
	v_pk_mul_f32 v[96:97], v[96:97], v[218:219]
	v_pk_mul_f32 v[90:91], v[90:91], v[220:221]
	v_pk_mul_f32 v[92:93], v[92:93], v[222:223]
	v_cvt_pk_bf16_f32 v168, v94, v95
	v_cvt_pk_bf16_f32 v169, v96, v97
	v_cvt_pk_bf16_f32 v170, v90, v91
	v_cvt_pk_bf16_f32 v171, v92, v93
	v_fma_f32 v86, v86, v180, v42
	v_fma_f32 v87, v87, v180, v43
	v_fma_f32 v88, v88, v180, v44
	v_fma_f32 v89, v89, v180, v45
	v_fma_f32 v82, v82, v180, v46
	v_fma_f32 v83, v83, v180, v47
	v_fma_f32 v84, v84, v180, v48
	v_fma_f32 v85, v85, v180, v49
	v_mul_f32_e32 v216, 0xbfb8aa3b, v86
	v_mul_f32_e32 v217, 0xbfb8aa3b, v87
	v_mul_f32_e32 v218, 0xbfb8aa3b, v88
	v_mul_f32_e32 v219, 0xbfb8aa3b, v89
	v_mul_f32_e32 v220, 0xbfb8aa3b, v82
	v_mul_f32_e32 v221, 0xbfb8aa3b, v83
	v_mul_f32_e32 v222, 0xbfb8aa3b, v84
	v_mul_f32_e32 v223, 0xbfb8aa3b, v85
	v_exp_f32_e32 v216, v216
	v_exp_f32_e32 v217, v217
	v_exp_f32_e32 v218, v218
	v_exp_f32_e32 v219, v219
	v_exp_f32_e32 v220, v220
	v_exp_f32_e32 v221, v221
	v_exp_f32_e32 v222, v222
	v_exp_f32_e32 v223, v223
	v_add_f32_e32 v216, 1.0, v216
	v_add_f32_e32 v217, 1.0, v217
	v_add_f32_e32 v218, 1.0, v218
	v_add_f32_e32 v219, 1.0, v219
	v_add_f32_e32 v220, 1.0, v220
	v_add_f32_e32 v221, 1.0, v221
	v_add_f32_e32 v222, 1.0, v222
	v_add_f32_e32 v223, 1.0, v223
	v_rcp_f32_e32 v216, v216
	v_rcp_f32_e32 v217, v217
	v_rcp_f32_e32 v218, v218
	v_rcp_f32_e32 v219, v219
	v_rcp_f32_e32 v220, v220
	v_rcp_f32_e32 v221, v221
	v_rcp_f32_e32 v222, v222
	v_rcp_f32_e32 v223, v223
	v_pk_mul_f32 v[86:87], v[86:87], v[216:217]
	v_pk_mul_f32 v[88:89], v[88:89], v[218:219]
	v_pk_mul_f32 v[82:83], v[82:83], v[220:221]
	v_pk_mul_f32 v[84:85], v[84:85], v[222:223]
	v_cvt_pk_bf16_f32 v184, v86, v87
	v_cvt_pk_bf16_f32 v185, v88, v89
	v_cvt_pk_bf16_f32 v186, v82, v83
	v_cvt_pk_bf16_f32 v187, v84, v85
	v_mov_b32_dpp v216, v168 quad_perm:[1,0,3,2] row_mask:0xf bank_mask:0xf
	v_mov_b32_dpp v217, v169 quad_perm:[1,0,3,2] row_mask:0xf bank_mask:0xf
	v_mov_b32_dpp v218, v170 quad_perm:[1,0,3,2] row_mask:0xf bank_mask:0xf
	v_mov_b32_dpp v219, v171 quad_perm:[1,0,3,2] row_mask:0xf bank_mask:0xf
	v_mov_b32_dpp v220, v184 quad_perm:[1,0,3,2] row_mask:0xf bank_mask:0xf
	v_mov_b32_dpp v221, v185 quad_perm:[1,0,3,2] row_mask:0xf bank_mask:0xf
	v_mov_b32_dpp v222, v186 quad_perm:[1,0,3,2] row_mask:0xf bank_mask:0xf
	v_mov_b32_dpp v223, v187 quad_perm:[1,0,3,2] row_mask:0xf bank_mask:0xf
	s_mov_b64 exec, s[62:63]
	v_mov_b32_e32 v168, v220
	v_mov_b32_e32 v169, v221
	v_mov_b32_e32 v170, v222
	v_mov_b32_e32 v171, v223
	s_mov_b64 exec, s[84:85]
	v_mov_b32_e32 v184, v216
	v_mov_b32_e32 v185, v217
	v_mov_b32_e32 v186, v218
	v_mov_b32_e32 v187, v219
	s_mov_b64 exec, -1
	s_add_u32 s80, s10, 0x60000
	s_addc_u32 s81, s11, 0
	s_add_u32 s82, s10, 0x62000
	s_addc_u32 s83, s11, 0
	global_store_dwordx4 v173, v[168:171], s[80:81]
	global_store_dwordx4 v173, v[184:187], s[82:83]
	v_fma_f32 v78, v78, v181, v26
	v_fma_f32 v79, v79, v181, v27
	v_fma_f32 v80, v80, v181, v28
	v_fma_f32 v81, v81, v181, v29
	v_fma_f32 v74, v74, v181, v30
	v_fma_f32 v75, v75, v181, v31
	v_fma_f32 v76, v76, v181, v32
	v_fma_f32 v77, v77, v181, v33
	v_mul_f32_e32 v216, 0xbfb8aa3b, v78
	v_mul_f32_e32 v217, 0xbfb8aa3b, v79
	v_mul_f32_e32 v218, 0xbfb8aa3b, v80
	v_mul_f32_e32 v219, 0xbfb8aa3b, v81
	v_mul_f32_e32 v220, 0xbfb8aa3b, v74
	v_mul_f32_e32 v221, 0xbfb8aa3b, v75
	v_mul_f32_e32 v222, 0xbfb8aa3b, v76
	v_mul_f32_e32 v223, 0xbfb8aa3b, v77
	v_exp_f32_e32 v216, v216
	v_exp_f32_e32 v217, v217
	v_exp_f32_e32 v218, v218
	v_exp_f32_e32 v219, v219
	v_exp_f32_e32 v220, v220
	v_exp_f32_e32 v221, v221
	v_exp_f32_e32 v222, v222
	v_exp_f32_e32 v223, v223
	v_add_f32_e32 v216, 1.0, v216
	v_add_f32_e32 v217, 1.0, v217
	v_add_f32_e32 v218, 1.0, v218
	v_add_f32_e32 v219, 1.0, v219
	v_add_f32_e32 v220, 1.0, v220
	v_add_f32_e32 v221, 1.0, v221
	v_add_f32_e32 v222, 1.0, v222
	v_add_f32_e32 v223, 1.0, v223
	v_rcp_f32_e32 v216, v216
	v_rcp_f32_e32 v217, v217
	v_rcp_f32_e32 v218, v218
	v_rcp_f32_e32 v219, v219
	v_rcp_f32_e32 v220, v220
	v_rcp_f32_e32 v221, v221
	v_rcp_f32_e32 v222, v222
	v_rcp_f32_e32 v223, v223
	v_pk_mul_f32 v[78:79], v[78:79], v[216:217]
	v_pk_mul_f32 v[80:81], v[80:81], v[218:219]
	v_pk_mul_f32 v[74:75], v[74:75], v[220:221]
	v_pk_mul_f32 v[76:77], v[76:77], v[222:223]
	v_cvt_pk_bf16_f32 v168, v78, v79
	v_cvt_pk_bf16_f32 v169, v80, v81
	v_cvt_pk_bf16_f32 v170, v74, v75
	v_cvt_pk_bf16_f32 v171, v76, v77
	v_fma_f32 v70, v70, v181, v42
	v_fma_f32 v71, v71, v181, v43
	v_fma_f32 v72, v72, v181, v44
	v_fma_f32 v73, v73, v181, v45
	v_fma_f32 v66, v66, v181, v46
	v_fma_f32 v67, v67, v181, v47
	v_fma_f32 v68, v68, v181, v48
	v_fma_f32 v69, v69, v181, v49
	v_mul_f32_e32 v216, 0xbfb8aa3b, v70
	v_mul_f32_e32 v217, 0xbfb8aa3b, v71
	v_mul_f32_e32 v218, 0xbfb8aa3b, v72
	v_mul_f32_e32 v219, 0xbfb8aa3b, v73
	v_mul_f32_e32 v220, 0xbfb8aa3b, v66
	v_mul_f32_e32 v221, 0xbfb8aa3b, v67
	v_mul_f32_e32 v222, 0xbfb8aa3b, v68
	v_mul_f32_e32 v223, 0xbfb8aa3b, v69
	v_exp_f32_e32 v216, v216
	v_exp_f32_e32 v217, v217
	v_exp_f32_e32 v218, v218
	v_exp_f32_e32 v219, v219
	v_exp_f32_e32 v220, v220
	v_exp_f32_e32 v221, v221
	v_exp_f32_e32 v222, v222
	v_exp_f32_e32 v223, v223
	v_add_f32_e32 v216, 1.0, v216
	v_add_f32_e32 v217, 1.0, v217
	v_add_f32_e32 v218, 1.0, v218
	v_add_f32_e32 v219, 1.0, v219
	v_add_f32_e32 v220, 1.0, v220
	v_add_f32_e32 v221, 1.0, v221
	v_add_f32_e32 v222, 1.0, v222
	v_add_f32_e32 v223, 1.0, v223
	v_rcp_f32_e32 v216, v216
	v_rcp_f32_e32 v217, v217
	v_rcp_f32_e32 v218, v218
	v_rcp_f32_e32 v219, v219
	v_rcp_f32_e32 v220, v220
	v_rcp_f32_e32 v221, v221
	v_rcp_f32_e32 v222, v222
	v_rcp_f32_e32 v223, v223
	v_pk_mul_f32 v[70:71], v[70:71], v[216:217]
	v_pk_mul_f32 v[72:73], v[72:73], v[218:219]
	v_pk_mul_f32 v[66:67], v[66:67], v[220:221]
	v_pk_mul_f32 v[68:69], v[68:69], v[222:223]
	v_cvt_pk_bf16_f32 v184, v70, v71
	v_cvt_pk_bf16_f32 v185, v72, v73
	v_cvt_pk_bf16_f32 v186, v66, v67
	v_cvt_pk_bf16_f32 v187, v68, v69
	v_mov_b32_dpp v216, v168 quad_perm:[1,0,3,2] row_mask:0xf bank_mask:0xf
	v_mov_b32_dpp v217, v169 quad_perm:[1,0,3,2] row_mask:0xf bank_mask:0xf
	v_mov_b32_dpp v218, v170 quad_perm:[1,0,3,2] row_mask:0xf bank_mask:0xf
	v_mov_b32_dpp v219, v171 quad_perm:[1,0,3,2] row_mask:0xf bank_mask:0xf
	v_mov_b32_dpp v220, v184 quad_perm:[1,0,3,2] row_mask:0xf bank_mask:0xf
	v_mov_b32_dpp v221, v185 quad_perm:[1,0,3,2] row_mask:0xf bank_mask:0xf
	v_mov_b32_dpp v222, v186 quad_perm:[1,0,3,2] row_mask:0xf bank_mask:0xf
	v_mov_b32_dpp v223, v187 quad_perm:[1,0,3,2] row_mask:0xf bank_mask:0xf
	s_mov_b64 exec, s[62:63]
	v_mov_b32_e32 v168, v220
	v_mov_b32_e32 v169, v221
	v_mov_b32_e32 v170, v222
	v_mov_b32_e32 v171, v223
	s_mov_b64 exec, s[84:85]
	v_mov_b32_e32 v184, v216
	v_mov_b32_e32 v185, v217
	v_mov_b32_e32 v186, v218
	v_mov_b32_e32 v187, v219
	s_mov_b64 exec, -1
	s_add_u32 s80, s10, 0x100000
	s_addc_u32 s81, s11, 0
	s_add_u32 s82, s10, 0x102000
	s_addc_u32 s83, s11, 0
	global_store_dwordx4 v173, v[168:171], s[80:81]
	global_store_dwordx4 v173, v[184:187], s[82:83]
	v_fma_f32 v62, v62, v182, v26
	v_fma_f32 v63, v63, v182, v27
	v_fma_f32 v64, v64, v182, v28
	v_fma_f32 v65, v65, v182, v29
	v_fma_f32 v58, v58, v182, v30
	v_fma_f32 v59, v59, v182, v31
	v_fma_f32 v60, v60, v182, v32
	v_fma_f32 v61, v61, v182, v33
	v_mul_f32_e32 v216, 0xbfb8aa3b, v62
	v_mul_f32_e32 v217, 0xbfb8aa3b, v63
	v_mul_f32_e32 v218, 0xbfb8aa3b, v64
	v_mul_f32_e32 v219, 0xbfb8aa3b, v65
	v_mul_f32_e32 v220, 0xbfb8aa3b, v58
	v_mul_f32_e32 v221, 0xbfb8aa3b, v59
	v_mul_f32_e32 v222, 0xbfb8aa3b, v60
	v_mul_f32_e32 v223, 0xbfb8aa3b, v61
	v_exp_f32_e32 v216, v216
	v_exp_f32_e32 v217, v217
	v_exp_f32_e32 v218, v218
	v_exp_f32_e32 v219, v219
	v_exp_f32_e32 v220, v220
	v_exp_f32_e32 v221, v221
	v_exp_f32_e32 v222, v222
	v_exp_f32_e32 v223, v223
	v_add_f32_e32 v216, 1.0, v216
	v_add_f32_e32 v217, 1.0, v217
	v_add_f32_e32 v218, 1.0, v218
	v_add_f32_e32 v219, 1.0, v219
	v_add_f32_e32 v220, 1.0, v220
	v_add_f32_e32 v221, 1.0, v221
	v_add_f32_e32 v222, 1.0, v222
	v_add_f32_e32 v223, 1.0, v223
	v_rcp_f32_e32 v216, v216
	v_rcp_f32_e32 v217, v217
	v_rcp_f32_e32 v218, v218
	v_rcp_f32_e32 v219, v219
	v_rcp_f32_e32 v220, v220
	v_rcp_f32_e32 v221, v221
	v_rcp_f32_e32 v222, v222
	v_rcp_f32_e32 v223, v223
	v_pk_mul_f32 v[62:63], v[62:63], v[216:217]
	v_pk_mul_f32 v[64:65], v[64:65], v[218:219]
	v_pk_mul_f32 v[58:59], v[58:59], v[220:221]
	v_pk_mul_f32 v[60:61], v[60:61], v[222:223]
	v_cvt_pk_bf16_f32 v168, v62, v63
	v_cvt_pk_bf16_f32 v169, v64, v65
	v_cvt_pk_bf16_f32 v170, v58, v59
	v_cvt_pk_bf16_f32 v171, v60, v61
	v_fma_f32 v54, v54, v182, v42
	v_fma_f32 v55, v55, v182, v43
	v_fma_f32 v56, v56, v182, v44
	v_fma_f32 v57, v57, v182, v45
	v_fma_f32 v50, v50, v182, v46
	v_fma_f32 v51, v51, v182, v47
	v_fma_f32 v52, v52, v182, v48
	v_fma_f32 v53, v53, v182, v49
	v_mul_f32_e32 v216, 0xbfb8aa3b, v54
	v_mul_f32_e32 v217, 0xbfb8aa3b, v55
	v_mul_f32_e32 v218, 0xbfb8aa3b, v56
	v_mul_f32_e32 v219, 0xbfb8aa3b, v57
	v_mul_f32_e32 v220, 0xbfb8aa3b, v50
	v_mul_f32_e32 v221, 0xbfb8aa3b, v51
	v_mul_f32_e32 v222, 0xbfb8aa3b, v52
	v_mul_f32_e32 v223, 0xbfb8aa3b, v53
	v_exp_f32_e32 v216, v216
	v_exp_f32_e32 v217, v217
	v_exp_f32_e32 v218, v218
	v_exp_f32_e32 v219, v219
	v_exp_f32_e32 v220, v220
	v_exp_f32_e32 v221, v221
	v_exp_f32_e32 v222, v222
	v_exp_f32_e32 v223, v223
	v_add_f32_e32 v216, 1.0, v216
	v_add_f32_e32 v217, 1.0, v217
	v_add_f32_e32 v218, 1.0, v218
	v_add_f32_e32 v219, 1.0, v219
	v_add_f32_e32 v220, 1.0, v220
	v_add_f32_e32 v221, 1.0, v221
	v_add_f32_e32 v222, 1.0, v222
	v_add_f32_e32 v223, 1.0, v223
	v_rcp_f32_e32 v216, v216
	v_rcp_f32_e32 v217, v217
	v_rcp_f32_e32 v218, v218
	v_rcp_f32_e32 v219, v219
	v_rcp_f32_e32 v220, v220
	v_rcp_f32_e32 v221, v221
	v_rcp_f32_e32 v222, v222
	v_rcp_f32_e32 v223, v223
	v_pk_mul_f32 v[54:55], v[54:55], v[216:217]
	v_pk_mul_f32 v[56:57], v[56:57], v[218:219]
	v_pk_mul_f32 v[50:51], v[50:51], v[220:221]
	v_pk_mul_f32 v[52:53], v[52:53], v[222:223]
	v_cvt_pk_bf16_f32 v184, v54, v55
	v_cvt_pk_bf16_f32 v185, v56, v57
	v_cvt_pk_bf16_f32 v186, v50, v51
	v_cvt_pk_bf16_f32 v187, v52, v53
	v_mov_b32_dpp v216, v168 quad_perm:[1,0,3,2] row_mask:0xf bank_mask:0xf
	v_mov_b32_dpp v217, v169 quad_perm:[1,0,3,2] row_mask:0xf bank_mask:0xf
	v_mov_b32_dpp v218, v170 quad_perm:[1,0,3,2] row_mask:0xf bank_mask:0xf
	v_mov_b32_dpp v219, v171 quad_perm:[1,0,3,2] row_mask:0xf bank_mask:0xf
	v_mov_b32_dpp v220, v184 quad_perm:[1,0,3,2] row_mask:0xf bank_mask:0xf
	v_mov_b32_dpp v221, v185 quad_perm:[1,0,3,2] row_mask:0xf bank_mask:0xf
	v_mov_b32_dpp v222, v186 quad_perm:[1,0,3,2] row_mask:0xf bank_mask:0xf
	v_mov_b32_dpp v223, v187 quad_perm:[1,0,3,2] row_mask:0xf bank_mask:0xf
	s_mov_b64 exec, s[62:63]
	v_mov_b32_e32 v168, v220
	v_mov_b32_e32 v169, v221
	v_mov_b32_e32 v170, v222
	v_mov_b32_e32 v171, v223
	s_mov_b64 exec, s[84:85]
	v_mov_b32_e32 v184, v216
	v_mov_b32_e32 v185, v217
	v_mov_b32_e32 v186, v218
	v_mov_b32_e32 v187, v219
	s_mov_b64 exec, -1
	s_add_u32 s80, s10, 0x120000
	s_addc_u32 s81, s11, 0
	s_add_u32 s82, s10, 0x122000
	s_addc_u32 s83, s11, 0
	global_store_dwordx4 v173, v[168:171], s[80:81]
	global_store_dwordx4 v173, v[184:187], s[82:83]
	v_fma_f32 v38, v38, v188, v26
	v_fma_f32 v39, v39, v188, v27
	v_fma_f32 v40, v40, v188, v28
	v_fma_f32 v41, v41, v188, v29
	v_fma_f32 v34, v34, v188, v30
	v_fma_f32 v35, v35, v188, v31
	v_fma_f32 v36, v36, v188, v32
	v_fma_f32 v37, v37, v188, v33
	v_mul_f32_e32 v216, 0xbfb8aa3b, v38
	v_mul_f32_e32 v217, 0xbfb8aa3b, v39
	v_mul_f32_e32 v218, 0xbfb8aa3b, v40
	v_mul_f32_e32 v219, 0xbfb8aa3b, v41
	v_mul_f32_e32 v220, 0xbfb8aa3b, v34
	v_mul_f32_e32 v221, 0xbfb8aa3b, v35
	v_mul_f32_e32 v222, 0xbfb8aa3b, v36
	v_mul_f32_e32 v223, 0xbfb8aa3b, v37
	v_exp_f32_e32 v216, v216
	v_exp_f32_e32 v217, v217
	v_exp_f32_e32 v218, v218
	v_exp_f32_e32 v219, v219
	v_exp_f32_e32 v220, v220
	v_exp_f32_e32 v221, v221
	v_exp_f32_e32 v222, v222
	v_exp_f32_e32 v223, v223
	v_add_f32_e32 v216, 1.0, v216
	v_add_f32_e32 v217, 1.0, v217
	v_add_f32_e32 v218, 1.0, v218
	v_add_f32_e32 v219, 1.0, v219
	v_add_f32_e32 v220, 1.0, v220
	v_add_f32_e32 v221, 1.0, v221
	v_add_f32_e32 v222, 1.0, v222
	v_add_f32_e32 v223, 1.0, v223
	v_rcp_f32_e32 v216, v216
	v_rcp_f32_e32 v217, v217
	v_rcp_f32_e32 v218, v218
	v_rcp_f32_e32 v219, v219
	v_rcp_f32_e32 v220, v220
	v_rcp_f32_e32 v221, v221
	v_rcp_f32_e32 v222, v222
	v_rcp_f32_e32 v223, v223
	v_pk_mul_f32 v[38:39], v[38:39], v[216:217]
	v_pk_mul_f32 v[40:41], v[40:41], v[218:219]
	v_pk_mul_f32 v[34:35], v[34:35], v[220:221]
	v_pk_mul_f32 v[36:37], v[36:37], v[222:223]
	v_cvt_pk_bf16_f32 v168, v38, v39
	v_cvt_pk_bf16_f32 v169, v40, v41
	v_cvt_pk_bf16_f32 v170, v34, v35
	v_cvt_pk_bf16_f32 v171, v36, v37
	v_fma_f32 v22, v22, v188, v42
	v_fma_f32 v23, v23, v188, v43
	v_fma_f32 v24, v24, v188, v44
	v_fma_f32 v25, v25, v188, v45
	v_fma_f32 v18, v18, v188, v46
	v_fma_f32 v19, v19, v188, v47
	v_fma_f32 v20, v20, v188, v48
	v_fma_f32 v21, v21, v188, v49
	v_mul_f32_e32 v216, 0xbfb8aa3b, v22
	v_mul_f32_e32 v217, 0xbfb8aa3b, v23
	v_mul_f32_e32 v218, 0xbfb8aa3b, v24
	v_mul_f32_e32 v219, 0xbfb8aa3b, v25
	v_mul_f32_e32 v220, 0xbfb8aa3b, v18
	v_mul_f32_e32 v221, 0xbfb8aa3b, v19
	v_mul_f32_e32 v222, 0xbfb8aa3b, v20
	v_mul_f32_e32 v223, 0xbfb8aa3b, v21
	v_exp_f32_e32 v216, v216
	v_exp_f32_e32 v217, v217
	v_exp_f32_e32 v218, v218
	v_exp_f32_e32 v219, v219
	v_exp_f32_e32 v220, v220
	v_exp_f32_e32 v221, v221
	v_exp_f32_e32 v222, v222
	v_exp_f32_e32 v223, v223
	v_add_f32_e32 v216, 1.0, v216
	v_add_f32_e32 v217, 1.0, v217
	v_add_f32_e32 v218, 1.0, v218
	v_add_f32_e32 v219, 1.0, v219
	v_add_f32_e32 v220, 1.0, v220
	v_add_f32_e32 v221, 1.0, v221
	v_add_f32_e32 v222, 1.0, v222
	v_add_f32_e32 v223, 1.0, v223
	v_rcp_f32_e32 v216, v216
	v_rcp_f32_e32 v217, v217
	v_rcp_f32_e32 v218, v218
	v_rcp_f32_e32 v219, v219
	v_rcp_f32_e32 v220, v220
	v_rcp_f32_e32 v221, v221
	v_rcp_f32_e32 v222, v222
	v_rcp_f32_e32 v223, v223
	v_pk_mul_f32 v[22:23], v[22:23], v[216:217]
	v_pk_mul_f32 v[24:25], v[24:25], v[218:219]
	v_pk_mul_f32 v[18:19], v[18:19], v[220:221]
	v_pk_mul_f32 v[20:21], v[20:21], v[222:223]
	v_cvt_pk_bf16_f32 v184, v22, v23
	v_cvt_pk_bf16_f32 v185, v24, v25
	v_cvt_pk_bf16_f32 v186, v18, v19
	v_cvt_pk_bf16_f32 v187, v20, v21
	v_mov_b32_dpp v216, v168 quad_perm:[1,0,3,2] row_mask:0xf bank_mask:0xf
	v_mov_b32_dpp v217, v169 quad_perm:[1,0,3,2] row_mask:0xf bank_mask:0xf
	v_mov_b32_dpp v218, v170 quad_perm:[1,0,3,2] row_mask:0xf bank_mask:0xf
	v_mov_b32_dpp v219, v171 quad_perm:[1,0,3,2] row_mask:0xf bank_mask:0xf
	v_mov_b32_dpp v220, v184 quad_perm:[1,0,3,2] row_mask:0xf bank_mask:0xf
	v_mov_b32_dpp v221, v185 quad_perm:[1,0,3,2] row_mask:0xf bank_mask:0xf
	v_mov_b32_dpp v222, v186 quad_perm:[1,0,3,2] row_mask:0xf bank_mask:0xf
	v_mov_b32_dpp v223, v187 quad_perm:[1,0,3,2] row_mask:0xf bank_mask:0xf
	s_mov_b64 exec, s[62:63]
	v_mov_b32_e32 v168, v220
	v_mov_b32_e32 v169, v221
	v_mov_b32_e32 v170, v222
	v_mov_b32_e32 v171, v223
	s_mov_b64 exec, s[84:85]
	v_mov_b32_e32 v184, v216
	v_mov_b32_e32 v185, v217
	v_mov_b32_e32 v186, v218
	v_mov_b32_e32 v187, v219
	s_mov_b64 exec, -1
	s_add_u32 s80, s10, 0x140000
	s_addc_u32 s81, s11, 0
	s_add_u32 s82, s10, 0x142000
	s_addc_u32 s83, s11, 0
	global_store_dwordx4 v173, v[168:171], s[80:81]
	global_store_dwordx4 v173, v[184:187], s[82:83]
	v_fma_f32 v14, v14, v189, v26
	v_fma_f32 v15, v15, v189, v27
	v_fma_f32 v16, v16, v189, v28
	v_fma_f32 v17, v17, v189, v29
	v_fma_f32 v10, v10, v189, v30
	v_fma_f32 v11, v11, v189, v31
	v_fma_f32 v12, v12, v189, v32
	v_fma_f32 v13, v13, v189, v33
	v_mul_f32_e32 v216, 0xbfb8aa3b, v14
	v_mul_f32_e32 v217, 0xbfb8aa3b, v15
	v_mul_f32_e32 v218, 0xbfb8aa3b, v16
	v_mul_f32_e32 v219, 0xbfb8aa3b, v17
	v_mul_f32_e32 v220, 0xbfb8aa3b, v10
	v_mul_f32_e32 v221, 0xbfb8aa3b, v11
	v_mul_f32_e32 v222, 0xbfb8aa3b, v12
	v_mul_f32_e32 v223, 0xbfb8aa3b, v13
	v_exp_f32_e32 v216, v216
	v_exp_f32_e32 v217, v217
	v_exp_f32_e32 v218, v218
	v_exp_f32_e32 v219, v219
	v_exp_f32_e32 v220, v220
	v_exp_f32_e32 v221, v221
	v_exp_f32_e32 v222, v222
	v_exp_f32_e32 v223, v223
	v_add_f32_e32 v216, 1.0, v216
	v_add_f32_e32 v217, 1.0, v217
	v_add_f32_e32 v218, 1.0, v218
	v_add_f32_e32 v219, 1.0, v219
	v_add_f32_e32 v220, 1.0, v220
	v_add_f32_e32 v221, 1.0, v221
	v_add_f32_e32 v222, 1.0, v222
	v_add_f32_e32 v223, 1.0, v223
	v_rcp_f32_e32 v216, v216
	v_rcp_f32_e32 v217, v217
	v_rcp_f32_e32 v218, v218
	v_rcp_f32_e32 v219, v219
	v_rcp_f32_e32 v220, v220
	v_rcp_f32_e32 v221, v221
	v_rcp_f32_e32 v222, v222
	v_rcp_f32_e32 v223, v223
	v_pk_mul_f32 v[14:15], v[14:15], v[216:217]
	v_pk_mul_f32 v[16:17], v[16:17], v[218:219]
	v_pk_mul_f32 v[10:11], v[10:11], v[220:221]
	v_pk_mul_f32 v[12:13], v[12:13], v[222:223]
	v_cvt_pk_bf16_f32 v168, v14, v15
	v_cvt_pk_bf16_f32 v169, v16, v17
	v_cvt_pk_bf16_f32 v170, v10, v11
	v_cvt_pk_bf16_f32 v171, v12, v13
	v_fma_f32 v6, v6, v189, v42
	v_fma_f32 v7, v7, v189, v43
	v_fma_f32 v8, v8, v189, v44
	v_fma_f32 v9, v9, v189, v45
	v_fma_f32 v2, v2, v189, v46
	v_fma_f32 v3, v3, v189, v47
	v_fma_f32 v4, v4, v189, v48
	v_fma_f32 v5, v5, v189, v49
	v_mul_f32_e32 v216, 0xbfb8aa3b, v6
	v_mul_f32_e32 v217, 0xbfb8aa3b, v7
	v_mul_f32_e32 v218, 0xbfb8aa3b, v8
	v_mul_f32_e32 v219, 0xbfb8aa3b, v9
	v_mul_f32_e32 v220, 0xbfb8aa3b, v2
	v_mul_f32_e32 v221, 0xbfb8aa3b, v3
	v_mul_f32_e32 v222, 0xbfb8aa3b, v4
	v_mul_f32_e32 v223, 0xbfb8aa3b, v5
	v_exp_f32_e32 v216, v216
	v_exp_f32_e32 v217, v217
	v_exp_f32_e32 v218, v218
	v_exp_f32_e32 v219, v219
	v_exp_f32_e32 v220, v220
	v_exp_f32_e32 v221, v221
	v_exp_f32_e32 v222, v222
	v_exp_f32_e32 v223, v223
	v_add_f32_e32 v216, 1.0, v216
	v_add_f32_e32 v217, 1.0, v217
	v_add_f32_e32 v218, 1.0, v218
	v_add_f32_e32 v219, 1.0, v219
	v_add_f32_e32 v220, 1.0, v220
	v_add_f32_e32 v221, 1.0, v221
	v_add_f32_e32 v222, 1.0, v222
	v_add_f32_e32 v223, 1.0, v223
	v_rcp_f32_e32 v216, v216
	v_rcp_f32_e32 v217, v217
	v_rcp_f32_e32 v218, v218
	v_rcp_f32_e32 v219, v219
	v_rcp_f32_e32 v220, v220
	v_rcp_f32_e32 v221, v221
	v_rcp_f32_e32 v222, v222
	v_rcp_f32_e32 v223, v223
	v_pk_mul_f32 v[6:7], v[6:7], v[216:217]
	v_pk_mul_f32 v[8:9], v[8:9], v[218:219]
	v_pk_mul_f32 v[2:3], v[2:3], v[220:221]
	v_pk_mul_f32 v[4:5], v[4:5], v[222:223]
	v_cvt_pk_bf16_f32 v184, v6, v7
	v_cvt_pk_bf16_f32 v185, v8, v9
	v_cvt_pk_bf16_f32 v186, v2, v3
	v_cvt_pk_bf16_f32 v187, v4, v5
	v_mov_b32_dpp v216, v168 quad_perm:[1,0,3,2] row_mask:0xf bank_mask:0xf
	v_mov_b32_dpp v217, v169 quad_perm:[1,0,3,2] row_mask:0xf bank_mask:0xf
	v_mov_b32_dpp v218, v170 quad_perm:[1,0,3,2] row_mask:0xf bank_mask:0xf
	v_mov_b32_dpp v219, v171 quad_perm:[1,0,3,2] row_mask:0xf bank_mask:0xf
	v_mov_b32_dpp v220, v184 quad_perm:[1,0,3,2] row_mask:0xf bank_mask:0xf
	v_mov_b32_dpp v221, v185 quad_perm:[1,0,3,2] row_mask:0xf bank_mask:0xf
	v_mov_b32_dpp v222, v186 quad_perm:[1,0,3,2] row_mask:0xf bank_mask:0xf
	v_mov_b32_dpp v223, v187 quad_perm:[1,0,3,2] row_mask:0xf bank_mask:0xf
	s_mov_b64 exec, s[62:63]
	v_mov_b32_e32 v168, v220
	v_mov_b32_e32 v169, v221
	v_mov_b32_e32 v170, v222
	v_mov_b32_e32 v171, v223
	s_mov_b64 exec, s[84:85]
	v_mov_b32_e32 v184, v216
	v_mov_b32_e32 v185, v217
	v_mov_b32_e32 v186, v218
	v_mov_b32_e32 v187, v219
	s_mov_b64 exec, -1
	s_add_u32 s80, s10, 0x160000
	s_addc_u32 s81, s11, 0
	s_add_u32 s82, s10, 0x162000
	s_addc_u32 s83, s11, 0
	global_store_dwordx4 v173, v[168:171], s[80:81]
	global_store_dwordx4 v173, v[184:187], s[82:83]
	s_branch .Lact1_hgin_done
.Lact1_hgin_id:
	s_waitcnt lgkmcnt(0)
	v_fma_f32 v142, v142, v176, v26
	v_fma_f32 v143, v143, v176, v27
	v_fma_f32 v144, v144, v176, v28
	v_fma_f32 v145, v145, v176, v29
	v_fma_f32 v138, v138, v176, v30
	v_fma_f32 v139, v139, v176, v31
	v_fma_f32 v140, v140, v176, v32
	v_fma_f32 v141, v141, v176, v33
	v_cvt_pk_bf16_f32 v168, v142, v143
	v_cvt_pk_bf16_f32 v169, v144, v145
	v_cvt_pk_bf16_f32 v170, v138, v139
	v_cvt_pk_bf16_f32 v171, v140, v141
	v_fma_f32 v134, v134, v176, v42
	v_fma_f32 v135, v135, v176, v43
	v_fma_f32 v136, v136, v176, v44
	v_fma_f32 v137, v137, v176, v45
	v_fma_f32 v130, v130, v176, v46
	v_fma_f32 v131, v131, v176, v47
	v_fma_f32 v132, v132, v176, v48
	v_fma_f32 v133, v133, v176, v49
	v_cvt_pk_bf16_f32 v184, v134, v135
	v_cvt_pk_bf16_f32 v185, v136, v137
	v_cvt_pk_bf16_f32 v186, v130, v131
	v_cvt_pk_bf16_f32 v187, v132, v133
	v_mov_b32_dpp v216, v168 quad_perm:[1,0,3,2] row_mask:0xf bank_mask:0xf
	v_mov_b32_dpp v217, v169 quad_perm:[1,0,3,2] row_mask:0xf bank_mask:0xf
	v_mov_b32_dpp v218, v170 quad_perm:[1,0,3,2] row_mask:0xf bank_mask:0xf
	v_mov_b32_dpp v219, v171 quad_perm:[1,0,3,2] row_mask:0xf bank_mask:0xf
	v_mov_b32_dpp v220, v184 quad_perm:[1,0,3,2] row_mask:0xf bank_mask:0xf
	v_mov_b32_dpp v221, v185 quad_perm:[1,0,3,2] row_mask:0xf bank_mask:0xf
	v_mov_b32_dpp v222, v186 quad_perm:[1,0,3,2] row_mask:0xf bank_mask:0xf
	v_mov_b32_dpp v223, v187 quad_perm:[1,0,3,2] row_mask:0xf bank_mask:0xf
	s_mov_b64 exec, s[62:63]
	v_mov_b32_e32 v168, v220
	v_mov_b32_e32 v169, v221
	v_mov_b32_e32 v170, v222
	v_mov_b32_e32 v171, v223
	s_mov_b64 exec, s[84:85]
	v_mov_b32_e32 v184, v216
	v_mov_b32_e32 v185, v217
	v_mov_b32_e32 v186, v218
	v_mov_b32_e32 v187, v219
	s_mov_b64 exec, -1
	s_add_u32 s80, s10, 0x0
	s_addc_u32 s81, s11, 0
	s_add_u32 s82, s10, 0x2000
	s_addc_u32 s83, s11, 0
	global_store_dwordx4 v173, v[168:171], s[80:81]
	global_store_dwordx4 v173, v[184:187], s[82:83]
	v_fma_f32 v126, v126, v177, v26
	v_fma_f32 v127, v127, v177, v27
	v_fma_f32 v128, v128, v177, v28
	v_fma_f32 v129, v129, v177, v29
	v_fma_f32 v122, v122, v177, v30
	v_fma_f32 v123, v123, v177, v31
	v_fma_f32 v124, v124, v177, v32
	v_fma_f32 v125, v125, v177, v33
	v_cvt_pk_bf16_f32 v168, v126, v127
	v_cvt_pk_bf16_f32 v169, v128, v129
	v_cvt_pk_bf16_f32 v170, v122, v123
	v_cvt_pk_bf16_f32 v171, v124, v125
	v_fma_f32 v118, v118, v177, v42
	v_fma_f32 v119, v119, v177, v43
	v_fma_f32 v120, v120, v177, v44
	v_fma_f32 v121, v121, v177, v45
	v_fma_f32 v114, v114, v177, v46
	v_fma_f32 v115, v115, v177, v47
	v_fma_f32 v116, v116, v177, v48
	v_fma_f32 v117, v117, v177, v49
	v_cvt_pk_bf16_f32 v184, v118, v119
	v_cvt_pk_bf16_f32 v185, v120, v121
	v_cvt_pk_bf16_f32 v186, v114, v115
	v_cvt_pk_bf16_f32 v187, v116, v117
	v_mov_b32_dpp v216, v168 quad_perm:[1,0,3,2] row_mask:0xf bank_mask:0xf
	v_mov_b32_dpp v217, v169 quad_perm:[1,0,3,2] row_mask:0xf bank_mask:0xf
	v_mov_b32_dpp v218, v170 quad_perm:[1,0,3,2] row_mask:0xf bank_mask:0xf
	v_mov_b32_dpp v219, v171 quad_perm:[1,0,3,2] row_mask:0xf bank_mask:0xf
	v_mov_b32_dpp v220, v184 quad_perm:[1,0,3,2] row_mask:0xf bank_mask:0xf
	v_mov_b32_dpp v221, v185 quad_perm:[1,0,3,2] row_mask:0xf bank_mask:0xf
	v_mov_b32_dpp v222, v186 quad_perm:[1,0,3,2] row_mask:0xf bank_mask:0xf
	v_mov_b32_dpp v223, v187 quad_perm:[1,0,3,2] row_mask:0xf bank_mask:0xf
	s_mov_b64 exec, s[62:63]
	v_mov_b32_e32 v168, v220
	v_mov_b32_e32 v169, v221
	v_mov_b32_e32 v170, v222
	v_mov_b32_e32 v171, v223
	s_mov_b64 exec, s[84:85]
	v_mov_b32_e32 v184, v216
	v_mov_b32_e32 v185, v217
	v_mov_b32_e32 v186, v218
	v_mov_b32_e32 v187, v219
	s_mov_b64 exec, -1
	s_add_u32 s80, s10, 0x20000
	s_addc_u32 s81, s11, 0
	s_add_u32 s82, s10, 0x22000
	s_addc_u32 s83, s11, 0
	global_store_dwordx4 v173, v[168:171], s[80:81]
	global_store_dwordx4 v173, v[184:187], s[82:83]
	v_fma_f32 v110, v110, v178, v26
	v_fma_f32 v111, v111, v178, v27
	v_fma_f32 v112, v112, v178, v28
	v_fma_f32 v113, v113, v178, v29
	v_fma_f32 v106, v106, v178, v30
	v_fma_f32 v107, v107, v178, v31
	v_fma_f32 v108, v108, v178, v32
	v_fma_f32 v109, v109, v178, v33
	v_cvt_pk_bf16_f32 v168, v110, v111
	v_cvt_pk_bf16_f32 v169, v112, v113
	v_cvt_pk_bf16_f32 v170, v106, v107
	v_cvt_pk_bf16_f32 v171, v108, v109
	v_fma_f32 v102, v102, v178, v42
	v_fma_f32 v103, v103, v178, v43
	v_fma_f32 v104, v104, v178, v44
	v_fma_f32 v105, v105, v178, v45
	v_fma_f32 v98, v98, v178, v46
	v_fma_f32 v99, v99, v178, v47
	v_fma_f32 v100, v100, v178, v48
	v_fma_f32 v101, v101, v178, v49
	v_cvt_pk_bf16_f32 v184, v102, v103
	v_cvt_pk_bf16_f32 v185, v104, v105
	v_cvt_pk_bf16_f32 v186, v98, v99
	v_cvt_pk_bf16_f32 v187, v100, v101
	v_mov_b32_dpp v216, v168 quad_perm:[1,0,3,2] row_mask:0xf bank_mask:0xf
	v_mov_b32_dpp v217, v169 quad_perm:[1,0,3,2] row_mask:0xf bank_mask:0xf
	v_mov_b32_dpp v218, v170 quad_perm:[1,0,3,2] row_mask:0xf bank_mask:0xf
	v_mov_b32_dpp v219, v171 quad_perm:[1,0,3,2] row_mask:0xf bank_mask:0xf
	v_mov_b32_dpp v220, v184 quad_perm:[1,0,3,2] row_mask:0xf bank_mask:0xf
	v_mov_b32_dpp v221, v185 quad_perm:[1,0,3,2] row_mask:0xf bank_mask:0xf
	v_mov_b32_dpp v222, v186 quad_perm:[1,0,3,2] row_mask:0xf bank_mask:0xf
	v_mov_b32_dpp v223, v187 quad_perm:[1,0,3,2] row_mask:0xf bank_mask:0xf
	s_mov_b64 exec, s[62:63]
	v_mov_b32_e32 v168, v220
	v_mov_b32_e32 v169, v221
	v_mov_b32_e32 v170, v222
	v_mov_b32_e32 v171, v223
	s_mov_b64 exec, s[84:85]
	v_mov_b32_e32 v184, v216
	v_mov_b32_e32 v185, v217
	v_mov_b32_e32 v186, v218
	v_mov_b32_e32 v187, v219
	s_mov_b64 exec, -1
	s_add_u32 s80, s10, 0x40000
	s_addc_u32 s81, s11, 0
	s_add_u32 s82, s10, 0x42000
	s_addc_u32 s83, s11, 0
	global_store_dwordx4 v173, v[168:171], s[80:81]
	global_store_dwordx4 v173, v[184:187], s[82:83]
	v_fma_f32 v94, v94, v180, v26
	v_fma_f32 v95, v95, v180, v27
	v_fma_f32 v96, v96, v180, v28
	v_fma_f32 v97, v97, v180, v29
	v_fma_f32 v90, v90, v180, v30
	v_fma_f32 v91, v91, v180, v31
	v_fma_f32 v92, v92, v180, v32
	v_fma_f32 v93, v93, v180, v33
	v_cvt_pk_bf16_f32 v168, v94, v95
	v_cvt_pk_bf16_f32 v169, v96, v97
	v_cvt_pk_bf16_f32 v170, v90, v91
	v_cvt_pk_bf16_f32 v171, v92, v93
	v_fma_f32 v86, v86, v180, v42
	v_fma_f32 v87, v87, v180, v43
	v_fma_f32 v88, v88, v180, v44
	v_fma_f32 v89, v89, v180, v45
	v_fma_f32 v82, v82, v180, v46
	v_fma_f32 v83, v83, v180, v47
	v_fma_f32 v84, v84, v180, v48
	v_fma_f32 v85, v85, v180, v49
	v_cvt_pk_bf16_f32 v184, v86, v87
	v_cvt_pk_bf16_f32 v185, v88, v89
	v_cvt_pk_bf16_f32 v186, v82, v83
	v_cvt_pk_bf16_f32 v187, v84, v85
	v_mov_b32_dpp v216, v168 quad_perm:[1,0,3,2] row_mask:0xf bank_mask:0xf
	v_mov_b32_dpp v217, v169 quad_perm:[1,0,3,2] row_mask:0xf bank_mask:0xf
	v_mov_b32_dpp v218, v170 quad_perm:[1,0,3,2] row_mask:0xf bank_mask:0xf
	v_mov_b32_dpp v219, v171 quad_perm:[1,0,3,2] row_mask:0xf bank_mask:0xf
	v_mov_b32_dpp v220, v184 quad_perm:[1,0,3,2] row_mask:0xf bank_mask:0xf
	v_mov_b32_dpp v221, v185 quad_perm:[1,0,3,2] row_mask:0xf bank_mask:0xf
	v_mov_b32_dpp v222, v186 quad_perm:[1,0,3,2] row_mask:0xf bank_mask:0xf
	v_mov_b32_dpp v223, v187 quad_perm:[1,0,3,2] row_mask:0xf bank_mask:0xf
	s_mov_b64 exec, s[62:63]
	v_mov_b32_e32 v168, v220
	v_mov_b32_e32 v169, v221
	v_mov_b32_e32 v170, v222
	v_mov_b32_e32 v171, v223
	s_mov_b64 exec, s[84:85]
	v_mov_b32_e32 v184, v216
	v_mov_b32_e32 v185, v217
	v_mov_b32_e32 v186, v218
	v_mov_b32_e32 v187, v219
	s_mov_b64 exec, -1
	s_add_u32 s80, s10, 0x60000
	s_addc_u32 s81, s11, 0
	s_add_u32 s82, s10, 0x62000
	s_addc_u32 s83, s11, 0
	global_store_dwordx4 v173, v[168:171], s[80:81]
	global_store_dwordx4 v173, v[184:187], s[82:83]
	v_fma_f32 v78, v78, v181, v26
	v_fma_f32 v79, v79, v181, v27
	v_fma_f32 v80, v80, v181, v28
	v_fma_f32 v81, v81, v181, v29
	v_fma_f32 v74, v74, v181, v30
	v_fma_f32 v75, v75, v181, v31
	v_fma_f32 v76, v76, v181, v32
	v_fma_f32 v77, v77, v181, v33
	v_cvt_pk_bf16_f32 v168, v78, v79
	v_cvt_pk_bf16_f32 v169, v80, v81
	v_cvt_pk_bf16_f32 v170, v74, v75
	v_cvt_pk_bf16_f32 v171, v76, v77
	v_fma_f32 v70, v70, v181, v42
	v_fma_f32 v71, v71, v181, v43
	v_fma_f32 v72, v72, v181, v44
	v_fma_f32 v73, v73, v181, v45
	v_fma_f32 v66, v66, v181, v46
	v_fma_f32 v67, v67, v181, v47
	v_fma_f32 v68, v68, v181, v48
	v_fma_f32 v69, v69, v181, v49
	v_cvt_pk_bf16_f32 v184, v70, v71
	v_cvt_pk_bf16_f32 v185, v72, v73
	v_cvt_pk_bf16_f32 v186, v66, v67
	v_cvt_pk_bf16_f32 v187, v68, v69
	v_mov_b32_dpp v216, v168 quad_perm:[1,0,3,2] row_mask:0xf bank_mask:0xf
	v_mov_b32_dpp v217, v169 quad_perm:[1,0,3,2] row_mask:0xf bank_mask:0xf
	v_mov_b32_dpp v218, v170 quad_perm:[1,0,3,2] row_mask:0xf bank_mask:0xf
	v_mov_b32_dpp v219, v171 quad_perm:[1,0,3,2] row_mask:0xf bank_mask:0xf
	v_mov_b32_dpp v220, v184 quad_perm:[1,0,3,2] row_mask:0xf bank_mask:0xf
	v_mov_b32_dpp v221, v185 quad_perm:[1,0,3,2] row_mask:0xf bank_mask:0xf
	v_mov_b32_dpp v222, v186 quad_perm:[1,0,3,2] row_mask:0xf bank_mask:0xf
	v_mov_b32_dpp v223, v187 quad_perm:[1,0,3,2] row_mask:0xf bank_mask:0xf
	s_mov_b64 exec, s[62:63]
	v_mov_b32_e32 v168, v220
	v_mov_b32_e32 v169, v221
	v_mov_b32_e32 v170, v222
	v_mov_b32_e32 v171, v223
	s_mov_b64 exec, s[84:85]
	v_mov_b32_e32 v184, v216
	v_mov_b32_e32 v185, v217
	v_mov_b32_e32 v186, v218
	v_mov_b32_e32 v187, v219
	s_mov_b64 exec, -1
	s_add_u32 s80, s10, 0x100000
	s_addc_u32 s81, s11, 0
	s_add_u32 s82, s10, 0x102000
	s_addc_u32 s83, s11, 0
	global_store_dwordx4 v173, v[168:171], s[80:81]
	global_store_dwordx4 v173, v[184:187], s[82:83]
	v_fma_f32 v62, v62, v182, v26
	v_fma_f32 v63, v63, v182, v27
	v_fma_f32 v64, v64, v182, v28
	v_fma_f32 v65, v65, v182, v29
	v_fma_f32 v58, v58, v182, v30
	v_fma_f32 v59, v59, v182, v31
	v_fma_f32 v60, v60, v182, v32
	v_fma_f32 v61, v61, v182, v33
	v_cvt_pk_bf16_f32 v168, v62, v63
	v_cvt_pk_bf16_f32 v169, v64, v65
	v_cvt_pk_bf16_f32 v170, v58, v59
	v_cvt_pk_bf16_f32 v171, v60, v61
	v_fma_f32 v54, v54, v182, v42
	v_fma_f32 v55, v55, v182, v43
	v_fma_f32 v56, v56, v182, v44
	v_fma_f32 v57, v57, v182, v45
	v_fma_f32 v50, v50, v182, v46
	v_fma_f32 v51, v51, v182, v47
	v_fma_f32 v52, v52, v182, v48
	v_fma_f32 v53, v53, v182, v49
	v_cvt_pk_bf16_f32 v184, v54, v55
	v_cvt_pk_bf16_f32 v185, v56, v57
	v_cvt_pk_bf16_f32 v186, v50, v51
	v_cvt_pk_bf16_f32 v187, v52, v53
	v_mov_b32_dpp v216, v168 quad_perm:[1,0,3,2] row_mask:0xf bank_mask:0xf
	v_mov_b32_dpp v217, v169 quad_perm:[1,0,3,2] row_mask:0xf bank_mask:0xf
	v_mov_b32_dpp v218, v170 quad_perm:[1,0,3,2] row_mask:0xf bank_mask:0xf
	v_mov_b32_dpp v219, v171 quad_perm:[1,0,3,2] row_mask:0xf bank_mask:0xf
	v_mov_b32_dpp v220, v184 quad_perm:[1,0,3,2] row_mask:0xf bank_mask:0xf
	v_mov_b32_dpp v221, v185 quad_perm:[1,0,3,2] row_mask:0xf bank_mask:0xf
	v_mov_b32_dpp v222, v186 quad_perm:[1,0,3,2] row_mask:0xf bank_mask:0xf
	v_mov_b32_dpp v223, v187 quad_perm:[1,0,3,2] row_mask:0xf bank_mask:0xf
	s_mov_b64 exec, s[62:63]
	v_mov_b32_e32 v168, v220
	v_mov_b32_e32 v169, v221
	v_mov_b32_e32 v170, v222
	v_mov_b32_e32 v171, v223
	s_mov_b64 exec, s[84:85]
	v_mov_b32_e32 v184, v216
	v_mov_b32_e32 v185, v217
	v_mov_b32_e32 v186, v218
	v_mov_b32_e32 v187, v219
	s_mov_b64 exec, -1
	s_add_u32 s80, s10, 0x120000
	s_addc_u32 s81, s11, 0
	s_add_u32 s82, s10, 0x122000
	s_addc_u32 s83, s11, 0
	global_store_dwordx4 v173, v[168:171], s[80:81]
	global_store_dwordx4 v173, v[184:187], s[82:83]
	v_fma_f32 v38, v38, v188, v26
	v_fma_f32 v39, v39, v188, v27
	v_fma_f32 v40, v40, v188, v28
	v_fma_f32 v41, v41, v188, v29
	v_fma_f32 v34, v34, v188, v30
	v_fma_f32 v35, v35, v188, v31
	v_fma_f32 v36, v36, v188, v32
	v_fma_f32 v37, v37, v188, v33
	v_cvt_pk_bf16_f32 v168, v38, v39
	v_cvt_pk_bf16_f32 v169, v40, v41
	v_cvt_pk_bf16_f32 v170, v34, v35
	v_cvt_pk_bf16_f32 v171, v36, v37
	v_fma_f32 v22, v22, v188, v42
	v_fma_f32 v23, v23, v188, v43
	v_fma_f32 v24, v24, v188, v44
	v_fma_f32 v25, v25, v188, v45
	v_fma_f32 v18, v18, v188, v46
	v_fma_f32 v19, v19, v188, v47
	v_fma_f32 v20, v20, v188, v48
	v_fma_f32 v21, v21, v188, v49
	v_cvt_pk_bf16_f32 v184, v22, v23
	v_cvt_pk_bf16_f32 v185, v24, v25
	v_cvt_pk_bf16_f32 v186, v18, v19
	v_cvt_pk_bf16_f32 v187, v20, v21
	v_mov_b32_dpp v216, v168 quad_perm:[1,0,3,2] row_mask:0xf bank_mask:0xf
	v_mov_b32_dpp v217, v169 quad_perm:[1,0,3,2] row_mask:0xf bank_mask:0xf
	v_mov_b32_dpp v218, v170 quad_perm:[1,0,3,2] row_mask:0xf bank_mask:0xf
	v_mov_b32_dpp v219, v171 quad_perm:[1,0,3,2] row_mask:0xf bank_mask:0xf
	v_mov_b32_dpp v220, v184 quad_perm:[1,0,3,2] row_mask:0xf bank_mask:0xf
	v_mov_b32_dpp v221, v185 quad_perm:[1,0,3,2] row_mask:0xf bank_mask:0xf
	v_mov_b32_dpp v222, v186 quad_perm:[1,0,3,2] row_mask:0xf bank_mask:0xf
	v_mov_b32_dpp v223, v187 quad_perm:[1,0,3,2] row_mask:0xf bank_mask:0xf
	s_mov_b64 exec, s[62:63]
	v_mov_b32_e32 v168, v220
	v_mov_b32_e32 v169, v221
	v_mov_b32_e32 v170, v222
	v_mov_b32_e32 v171, v223
	s_mov_b64 exec, s[84:85]
	v_mov_b32_e32 v184, v216
	v_mov_b32_e32 v185, v217
	v_mov_b32_e32 v186, v218
	v_mov_b32_e32 v187, v219
	s_mov_b64 exec, -1
	s_add_u32 s80, s10, 0x140000
	s_addc_u32 s81, s11, 0
	s_add_u32 s82, s10, 0x142000
	s_addc_u32 s83, s11, 0
	global_store_dwordx4 v173, v[168:171], s[80:81]
	global_store_dwordx4 v173, v[184:187], s[82:83]
	v_fma_f32 v14, v14, v189, v26
	v_fma_f32 v15, v15, v189, v27
	v_fma_f32 v16, v16, v189, v28
	v_fma_f32 v17, v17, v189, v29
	v_fma_f32 v10, v10, v189, v30
	v_fma_f32 v11, v11, v189, v31
	v_fma_f32 v12, v12, v189, v32
	v_fma_f32 v13, v13, v189, v33
	v_cvt_pk_bf16_f32 v168, v14, v15
	v_cvt_pk_bf16_f32 v169, v16, v17
	v_cvt_pk_bf16_f32 v170, v10, v11
	v_cvt_pk_bf16_f32 v171, v12, v13
	v_fma_f32 v6, v6, v189, v42
	v_fma_f32 v7, v7, v189, v43
	v_fma_f32 v8, v8, v189, v44
	v_fma_f32 v9, v9, v189, v45
	v_fma_f32 v2, v2, v189, v46
	v_fma_f32 v3, v3, v189, v47
	v_fma_f32 v4, v4, v189, v48
	v_fma_f32 v5, v5, v189, v49
	v_cvt_pk_bf16_f32 v184, v6, v7
	v_cvt_pk_bf16_f32 v185, v8, v9
	v_cvt_pk_bf16_f32 v186, v2, v3
	v_cvt_pk_bf16_f32 v187, v4, v5
	v_mov_b32_dpp v216, v168 quad_perm:[1,0,3,2] row_mask:0xf bank_mask:0xf
	v_mov_b32_dpp v217, v169 quad_perm:[1,0,3,2] row_mask:0xf bank_mask:0xf
	v_mov_b32_dpp v218, v170 quad_perm:[1,0,3,2] row_mask:0xf bank_mask:0xf
	v_mov_b32_dpp v219, v171 quad_perm:[1,0,3,2] row_mask:0xf bank_mask:0xf
	v_mov_b32_dpp v220, v184 quad_perm:[1,0,3,2] row_mask:0xf bank_mask:0xf
	v_mov_b32_dpp v221, v185 quad_perm:[1,0,3,2] row_mask:0xf bank_mask:0xf
	v_mov_b32_dpp v222, v186 quad_perm:[1,0,3,2] row_mask:0xf bank_mask:0xf
	v_mov_b32_dpp v223, v187 quad_perm:[1,0,3,2] row_mask:0xf bank_mask:0xf
	s_mov_b64 exec, s[62:63]
	v_mov_b32_e32 v168, v220
	v_mov_b32_e32 v169, v221
	v_mov_b32_e32 v170, v222
	v_mov_b32_e32 v171, v223
	s_mov_b64 exec, s[84:85]
	v_mov_b32_e32 v184, v216
	v_mov_b32_e32 v185, v217
	v_mov_b32_e32 v186, v218
	v_mov_b32_e32 v187, v219
	s_mov_b64 exec, -1
	s_add_u32 s80, s10, 0x160000
	s_addc_u32 s81, s11, 0
	s_add_u32 s82, s10, 0x162000
	s_addc_u32 s83, s11, 0
	global_store_dwordx4 v173, v[168:171], s[80:81]
	global_store_dwordx4 v173, v[184:187], s[82:83]
	s_branch .Lact1_hgin_done
.Lact1_hgin_kk:
	v_lshlrev_b32_e32 v215, 2, v215
	s_add_u32 s80, s18, 0xfffff000
	s_addc_u32 s81, s19, -1
	global_load_dwordx4 v[224:227], v215, s[80:81] offset:0
	global_load_dwordx4 v[228:231], v215, s[80:81] offset:16
	global_load_dwordx4 v[232:235], v215, s[80:81] offset:128
	global_load_dwordx4 v[236:239], v215, s[80:81] offset:144
	s_waitcnt vmcnt(0) lgkmcnt(0)
	v_sub_f32_e32 v224, 1.0, v224
	v_sub_f32_e32 v225, 1.0, v225
	v_sub_f32_e32 v226, 1.0, v226
	v_sub_f32_e32 v227, 1.0, v227
	v_sub_f32_e32 v228, 1.0, v228
	v_sub_f32_e32 v229, 1.0, v229
	v_sub_f32_e32 v230, 1.0, v230
	v_sub_f32_e32 v231, 1.0, v231
	v_sub_f32_e32 v232, 1.0, v232
	v_sub_f32_e32 v233, 1.0, v233
	v_sub_f32_e32 v234, 1.0, v234
	v_sub_f32_e32 v235, 1.0, v235
	v_sub_f32_e32 v236, 1.0, v236
	v_sub_f32_e32 v237, 1.0, v237
	v_sub_f32_e32 v238, 1.0, v238
	v_sub_f32_e32 v239, 1.0, v239
	v_fma_f32 v142, v142, v176, v26
	v_fma_f32 v143, v143, v176, v27
	v_fma_f32 v144, v144, v176, v28
	v_fma_f32 v145, v145, v176, v29
	v_fma_f32 v138, v138, v176, v30
	v_fma_f32 v139, v139, v176, v31
	v_fma_f32 v140, v140, v176, v32
	v_fma_f32 v141, v141, v176, v33
	v_mul_f32_e32 v216, 0x3fb8aa3b, v142
	v_mul_f32_e32 v217, 0x3fb8aa3b, v143
	v_mul_f32_e32 v218, 0x3fb8aa3b, v144
	v_mul_f32_e32 v219, 0x3fb8aa3b, v145
	v_mul_f32_e32 v220, 0x3fb8aa3b, v138
	v_mul_f32_e32 v221, 0x3fb8aa3b, v139
	v_mul_f32_e32 v222, 0x3fb8aa3b, v140
	v_mul_f32_e32 v223, 0x3fb8aa3b, v141
	v_exp_f32_e32 v216, v216
	v_exp_f32_e32 v217, v217
	v_exp_f32_e32 v218, v218
	v_exp_f32_e32 v219, v219
	v_exp_f32_e32 v220, v220
	v_exp_f32_e32 v221, v221
	v_exp_f32_e32 v222, v222
	v_exp_f32_e32 v223, v223
	v_add_f32_e32 v216, 1.0, v216
	v_add_f32_e32 v217, 1.0, v217
	v_add_f32_e32 v218, 1.0, v218
	v_add_f32_e32 v219, 1.0, v219
	v_add_f32_e32 v220, 1.0, v220
	v_add_f32_e32 v221, 1.0, v221
	v_add_f32_e32 v222, 1.0, v222
	v_add_f32_e32 v223, 1.0, v223
	v_rcp_f32_e32 v216, v216
	v_rcp_f32_e32 v217, v217
	v_rcp_f32_e32 v218, v218
	v_rcp_f32_e32 v219, v219
	v_rcp_f32_e32 v220, v220
	v_rcp_f32_e32 v221, v221
	v_rcp_f32_e32 v222, v222
	v_rcp_f32_e32 v223, v223
	v_mul_f32_e32 v216, v216, v224
	v_mul_f32_e32 v217, v217, v225
	v_mul_f32_e32 v218, v218, v226
	v_mul_f32_e32 v219, v219, v227
	v_mul_f32_e32 v220, v220, v228
	v_mul_f32_e32 v221, v221, v229
	v_mul_f32_e32 v222, v222, v230
	v_mul_f32_e32 v223, v223, v231
	v_cvt_pk_f16_f32 v168, v216, v217
	v_cvt_pk_f16_f32 v169, v218, v219
	v_cvt_pk_f16_f32 v170, v220, v221
	v_cvt_pk_f16_f32 v171, v222, v223
	v_fma_f32 v134, v134, v176, v42
	v_fma_f32 v135, v135, v176, v43
	v_fma_f32 v136, v136, v176, v44
	v_fma_f32 v137, v137, v176, v45
	v_fma_f32 v130, v130, v176, v46
	v_fma_f32 v131, v131, v176, v47
	v_fma_f32 v132, v132, v176, v48
	v_fma_f32 v133, v133, v176, v49
	v_mul_f32_e32 v216, 0x3fb8aa3b, v134
	v_mul_f32_e32 v217, 0x3fb8aa3b, v135
	v_mul_f32_e32 v218, 0x3fb8aa3b, v136
	v_mul_f32_e32 v219, 0x3fb8aa3b, v137
	v_mul_f32_e32 v220, 0x3fb8aa3b, v130
	v_mul_f32_e32 v221, 0x3fb8aa3b, v131
	v_mul_f32_e32 v222, 0x3fb8aa3b, v132
	v_mul_f32_e32 v223, 0x3fb8aa3b, v133
	v_exp_f32_e32 v216, v216
	v_exp_f32_e32 v217, v217
	v_exp_f32_e32 v218, v218
	v_exp_f32_e32 v219, v219
	v_exp_f32_e32 v220, v220
	v_exp_f32_e32 v221, v221
	v_exp_f32_e32 v222, v222
	v_exp_f32_e32 v223, v223
	v_add_f32_e32 v216, 1.0, v216
	v_add_f32_e32 v217, 1.0, v217
	v_add_f32_e32 v218, 1.0, v218
	v_add_f32_e32 v219, 1.0, v219
	v_add_f32_e32 v220, 1.0, v220
	v_add_f32_e32 v221, 1.0, v221
	v_add_f32_e32 v222, 1.0, v222
	v_add_f32_e32 v223, 1.0, v223
	v_rcp_f32_e32 v216, v216
	v_rcp_f32_e32 v217, v217
	v_rcp_f32_e32 v218, v218
	v_rcp_f32_e32 v219, v219
	v_rcp_f32_e32 v220, v220
	v_rcp_f32_e32 v221, v221
	v_rcp_f32_e32 v222, v222
	v_rcp_f32_e32 v223, v223
	v_mul_f32_e32 v216, v216, v232
	v_mul_f32_e32 v217, v217, v233
	v_mul_f32_e32 v218, v218, v234
	v_mul_f32_e32 v219, v219, v235
	v_mul_f32_e32 v220, v220, v236
	v_mul_f32_e32 v221, v221, v237
	v_mul_f32_e32 v222, v222, v238
	v_mul_f32_e32 v223, v223, v239
	v_cvt_pk_f16_f32 v184, v216, v217
	v_cvt_pk_f16_f32 v185, v218, v219
	v_cvt_pk_f16_f32 v186, v220, v221
	v_cvt_pk_f16_f32 v187, v222, v223
	v_mov_b32_dpp v216, v168 quad_perm:[1,0,3,2] row_mask:0xf bank_mask:0xf
	v_mov_b32_dpp v217, v169 quad_perm:[1,0,3,2] row_mask:0xf bank_mask:0xf
	v_mov_b32_dpp v218, v170 quad_perm:[1,0,3,2] row_mask:0xf bank_mask:0xf
	v_mov_b32_dpp v219, v171 quad_perm:[1,0,3,2] row_mask:0xf bank_mask:0xf
	v_mov_b32_dpp v220, v184 quad_perm:[1,0,3,2] row_mask:0xf bank_mask:0xf
	v_mov_b32_dpp v221, v185 quad_perm:[1,0,3,2] row_mask:0xf bank_mask:0xf
	v_mov_b32_dpp v222, v186 quad_perm:[1,0,3,2] row_mask:0xf bank_mask:0xf
	v_mov_b32_dpp v223, v187 quad_perm:[1,0,3,2] row_mask:0xf bank_mask:0xf
	s_mov_b64 exec, s[62:63]
	v_mov_b32_e32 v168, v220
	v_mov_b32_e32 v169, v221
	v_mov_b32_e32 v170, v222
	v_mov_b32_e32 v171, v223
	s_mov_b64 exec, s[84:85]
	v_mov_b32_e32 v184, v216
	v_mov_b32_e32 v185, v217
	v_mov_b32_e32 v186, v218
	v_mov_b32_e32 v187, v219
	s_mov_b64 exec, -1
	s_add_u32 s80, s10, 0x0
	s_addc_u32 s81, s11, 0
	s_add_u32 s82, s10, 0x2000
	s_addc_u32 s83, s11, 0
	global_store_dwordx4 v173, v[168:171], s[80:81]
	global_store_dwordx4 v173, v[184:187], s[82:83]
	v_fma_f32 v126, v126, v177, v26
	v_fma_f32 v127, v127, v177, v27
	v_fma_f32 v128, v128, v177, v28
	v_fma_f32 v129, v129, v177, v29
	v_fma_f32 v122, v122, v177, v30
	v_fma_f32 v123, v123, v177, v31
	v_fma_f32 v124, v124, v177, v32
	v_fma_f32 v125, v125, v177, v33
	v_mul_f32_e32 v216, 0x3fb8aa3b, v126
	v_mul_f32_e32 v217, 0x3fb8aa3b, v127
	v_mul_f32_e32 v218, 0x3fb8aa3b, v128
	v_mul_f32_e32 v219, 0x3fb8aa3b, v129
	v_mul_f32_e32 v220, 0x3fb8aa3b, v122
	v_mul_f32_e32 v221, 0x3fb8aa3b, v123
	v_mul_f32_e32 v222, 0x3fb8aa3b, v124
	v_mul_f32_e32 v223, 0x3fb8aa3b, v125
	v_exp_f32_e32 v216, v216
	v_exp_f32_e32 v217, v217
	v_exp_f32_e32 v218, v218
	v_exp_f32_e32 v219, v219
	v_exp_f32_e32 v220, v220
	v_exp_f32_e32 v221, v221
	v_exp_f32_e32 v222, v222
	v_exp_f32_e32 v223, v223
	v_add_f32_e32 v216, 1.0, v216
	v_add_f32_e32 v217, 1.0, v217
	v_add_f32_e32 v218, 1.0, v218
	v_add_f32_e32 v219, 1.0, v219
	v_add_f32_e32 v220, 1.0, v220
	v_add_f32_e32 v221, 1.0, v221
	v_add_f32_e32 v222, 1.0, v222
	v_add_f32_e32 v223, 1.0, v223
	v_rcp_f32_e32 v216, v216
	v_rcp_f32_e32 v217, v217
	v_rcp_f32_e32 v218, v218
	v_rcp_f32_e32 v219, v219
	v_rcp_f32_e32 v220, v220
	v_rcp_f32_e32 v221, v221
	v_rcp_f32_e32 v222, v222
	v_rcp_f32_e32 v223, v223
	v_mul_f32_e32 v216, v216, v224
	v_mul_f32_e32 v217, v217, v225
	v_mul_f32_e32 v218, v218, v226
	v_mul_f32_e32 v219, v219, v227
	v_mul_f32_e32 v220, v220, v228
	v_mul_f32_e32 v221, v221, v229
	v_mul_f32_e32 v222, v222, v230
	v_mul_f32_e32 v223, v223, v231
	v_cvt_pk_f16_f32 v168, v216, v217
	v_cvt_pk_f16_f32 v169, v218, v219
	v_cvt_pk_f16_f32 v170, v220, v221
	v_cvt_pk_f16_f32 v171, v222, v223
	v_fma_f32 v118, v118, v177, v42
	v_fma_f32 v119, v119, v177, v43
	v_fma_f32 v120, v120, v177, v44
	v_fma_f32 v121, v121, v177, v45
	v_fma_f32 v114, v114, v177, v46
	v_fma_f32 v115, v115, v177, v47
	v_fma_f32 v116, v116, v177, v48
	v_fma_f32 v117, v117, v177, v49
	v_mul_f32_e32 v216, 0x3fb8aa3b, v118
	v_mul_f32_e32 v217, 0x3fb8aa3b, v119
	v_mul_f32_e32 v218, 0x3fb8aa3b, v120
	v_mul_f32_e32 v219, 0x3fb8aa3b, v121
	v_mul_f32_e32 v220, 0x3fb8aa3b, v114
	v_mul_f32_e32 v221, 0x3fb8aa3b, v115
	v_mul_f32_e32 v222, 0x3fb8aa3b, v116
	v_mul_f32_e32 v223, 0x3fb8aa3b, v117
	v_exp_f32_e32 v216, v216
	v_exp_f32_e32 v217, v217
	v_exp_f32_e32 v218, v218
	v_exp_f32_e32 v219, v219
	v_exp_f32_e32 v220, v220
	v_exp_f32_e32 v221, v221
	v_exp_f32_e32 v222, v222
	v_exp_f32_e32 v223, v223
	v_add_f32_e32 v216, 1.0, v216
	v_add_f32_e32 v217, 1.0, v217
	v_add_f32_e32 v218, 1.0, v218
	v_add_f32_e32 v219, 1.0, v219
	v_add_f32_e32 v220, 1.0, v220
	v_add_f32_e32 v221, 1.0, v221
	v_add_f32_e32 v222, 1.0, v222
	v_add_f32_e32 v223, 1.0, v223
	v_rcp_f32_e32 v216, v216
	v_rcp_f32_e32 v217, v217
	v_rcp_f32_e32 v218, v218
	v_rcp_f32_e32 v219, v219
	v_rcp_f32_e32 v220, v220
	v_rcp_f32_e32 v221, v221
	v_rcp_f32_e32 v222, v222
	v_rcp_f32_e32 v223, v223
	v_mul_f32_e32 v216, v216, v232
	v_mul_f32_e32 v217, v217, v233
	v_mul_f32_e32 v218, v218, v234
	v_mul_f32_e32 v219, v219, v235
	v_mul_f32_e32 v220, v220, v236
	v_mul_f32_e32 v221, v221, v237
	v_mul_f32_e32 v222, v222, v238
	v_mul_f32_e32 v223, v223, v239
	v_cvt_pk_f16_f32 v184, v216, v217
	v_cvt_pk_f16_f32 v185, v218, v219
	v_cvt_pk_f16_f32 v186, v220, v221
	v_cvt_pk_f16_f32 v187, v222, v223
	v_mov_b32_dpp v216, v168 quad_perm:[1,0,3,2] row_mask:0xf bank_mask:0xf
	v_mov_b32_dpp v217, v169 quad_perm:[1,0,3,2] row_mask:0xf bank_mask:0xf
	v_mov_b32_dpp v218, v170 quad_perm:[1,0,3,2] row_mask:0xf bank_mask:0xf
	v_mov_b32_dpp v219, v171 quad_perm:[1,0,3,2] row_mask:0xf bank_mask:0xf
	v_mov_b32_dpp v220, v184 quad_perm:[1,0,3,2] row_mask:0xf bank_mask:0xf
	v_mov_b32_dpp v221, v185 quad_perm:[1,0,3,2] row_mask:0xf bank_mask:0xf
	v_mov_b32_dpp v222, v186 quad_perm:[1,0,3,2] row_mask:0xf bank_mask:0xf
	v_mov_b32_dpp v223, v187 quad_perm:[1,0,3,2] row_mask:0xf bank_mask:0xf
	s_mov_b64 exec, s[62:63]
	v_mov_b32_e32 v168, v220
	v_mov_b32_e32 v169, v221
	v_mov_b32_e32 v170, v222
	v_mov_b32_e32 v171, v223
	s_mov_b64 exec, s[84:85]
	v_mov_b32_e32 v184, v216
	v_mov_b32_e32 v185, v217
	v_mov_b32_e32 v186, v218
	v_mov_b32_e32 v187, v219
	s_mov_b64 exec, -1
	s_add_u32 s80, s10, 0x20000
	s_addc_u32 s81, s11, 0
	s_add_u32 s82, s10, 0x22000
	s_addc_u32 s83, s11, 0
	global_store_dwordx4 v173, v[168:171], s[80:81]
	global_store_dwordx4 v173, v[184:187], s[82:83]
	v_fma_f32 v110, v110, v178, v26
	v_fma_f32 v111, v111, v178, v27
	v_fma_f32 v112, v112, v178, v28
	v_fma_f32 v113, v113, v178, v29
	v_fma_f32 v106, v106, v178, v30
	v_fma_f32 v107, v107, v178, v31
	v_fma_f32 v108, v108, v178, v32
	v_fma_f32 v109, v109, v178, v33
	v_mul_f32_e32 v216, 0x3fb8aa3b, v110
	v_mul_f32_e32 v217, 0x3fb8aa3b, v111
	v_mul_f32_e32 v218, 0x3fb8aa3b, v112
	v_mul_f32_e32 v219, 0x3fb8aa3b, v113
	v_mul_f32_e32 v220, 0x3fb8aa3b, v106
	v_mul_f32_e32 v221, 0x3fb8aa3b, v107
	v_mul_f32_e32 v222, 0x3fb8aa3b, v108
	v_mul_f32_e32 v223, 0x3fb8aa3b, v109
	v_exp_f32_e32 v216, v216
	v_exp_f32_e32 v217, v217
	v_exp_f32_e32 v218, v218
	v_exp_f32_e32 v219, v219
	v_exp_f32_e32 v220, v220
	v_exp_f32_e32 v221, v221
	v_exp_f32_e32 v222, v222
	v_exp_f32_e32 v223, v223
	v_add_f32_e32 v216, 1.0, v216
	v_add_f32_e32 v217, 1.0, v217
	v_add_f32_e32 v218, 1.0, v218
	v_add_f32_e32 v219, 1.0, v219
	v_add_f32_e32 v220, 1.0, v220
	v_add_f32_e32 v221, 1.0, v221
	v_add_f32_e32 v222, 1.0, v222
	v_add_f32_e32 v223, 1.0, v223
	v_rcp_f32_e32 v216, v216
	v_rcp_f32_e32 v217, v217
	v_rcp_f32_e32 v218, v218
	v_rcp_f32_e32 v219, v219
	v_rcp_f32_e32 v220, v220
	v_rcp_f32_e32 v221, v221
	v_rcp_f32_e32 v222, v222
	v_rcp_f32_e32 v223, v223
	v_mul_f32_e32 v216, v216, v224
	v_mul_f32_e32 v217, v217, v225
	v_mul_f32_e32 v218, v218, v226
	v_mul_f32_e32 v219, v219, v227
	v_mul_f32_e32 v220, v220, v228
	v_mul_f32_e32 v221, v221, v229
	v_mul_f32_e32 v222, v222, v230
	v_mul_f32_e32 v223, v223, v231
	v_cvt_pk_f16_f32 v168, v216, v217
	v_cvt_pk_f16_f32 v169, v218, v219
	v_cvt_pk_f16_f32 v170, v220, v221
	v_cvt_pk_f16_f32 v171, v222, v223
	v_fma_f32 v102, v102, v178, v42
	v_fma_f32 v103, v103, v178, v43
	v_fma_f32 v104, v104, v178, v44
	v_fma_f32 v105, v105, v178, v45
	v_fma_f32 v98, v98, v178, v46
	v_fma_f32 v99, v99, v178, v47
	v_fma_f32 v100, v100, v178, v48
	v_fma_f32 v101, v101, v178, v49
	v_mul_f32_e32 v216, 0x3fb8aa3b, v102
	v_mul_f32_e32 v217, 0x3fb8aa3b, v103
	v_mul_f32_e32 v218, 0x3fb8aa3b, v104
	v_mul_f32_e32 v219, 0x3fb8aa3b, v105
	v_mul_f32_e32 v220, 0x3fb8aa3b, v98
	v_mul_f32_e32 v221, 0x3fb8aa3b, v99
	v_mul_f32_e32 v222, 0x3fb8aa3b, v100
	v_mul_f32_e32 v223, 0x3fb8aa3b, v101
	v_exp_f32_e32 v216, v216
	v_exp_f32_e32 v217, v217
	v_exp_f32_e32 v218, v218
	v_exp_f32_e32 v219, v219
	v_exp_f32_e32 v220, v220
	v_exp_f32_e32 v221, v221
	v_exp_f32_e32 v222, v222
	v_exp_f32_e32 v223, v223
	v_add_f32_e32 v216, 1.0, v216
	v_add_f32_e32 v217, 1.0, v217
	v_add_f32_e32 v218, 1.0, v218
	v_add_f32_e32 v219, 1.0, v219
	v_add_f32_e32 v220, 1.0, v220
	v_add_f32_e32 v221, 1.0, v221
	v_add_f32_e32 v222, 1.0, v222
	v_add_f32_e32 v223, 1.0, v223
	v_rcp_f32_e32 v216, v216
	v_rcp_f32_e32 v217, v217
	v_rcp_f32_e32 v218, v218
	v_rcp_f32_e32 v219, v219
	v_rcp_f32_e32 v220, v220
	v_rcp_f32_e32 v221, v221
	v_rcp_f32_e32 v222, v222
	v_rcp_f32_e32 v223, v223
	v_mul_f32_e32 v216, v216, v232
	v_mul_f32_e32 v217, v217, v233
	v_mul_f32_e32 v218, v218, v234
	v_mul_f32_e32 v219, v219, v235
	v_mul_f32_e32 v220, v220, v236
	v_mul_f32_e32 v221, v221, v237
	v_mul_f32_e32 v222, v222, v238
	v_mul_f32_e32 v223, v223, v239
	v_cvt_pk_f16_f32 v184, v216, v217
	v_cvt_pk_f16_f32 v185, v218, v219
	v_cvt_pk_f16_f32 v186, v220, v221
	v_cvt_pk_f16_f32 v187, v222, v223
	v_mov_b32_dpp v216, v168 quad_perm:[1,0,3,2] row_mask:0xf bank_mask:0xf
	v_mov_b32_dpp v217, v169 quad_perm:[1,0,3,2] row_mask:0xf bank_mask:0xf
	v_mov_b32_dpp v218, v170 quad_perm:[1,0,3,2] row_mask:0xf bank_mask:0xf
	v_mov_b32_dpp v219, v171 quad_perm:[1,0,3,2] row_mask:0xf bank_mask:0xf
	v_mov_b32_dpp v220, v184 quad_perm:[1,0,3,2] row_mask:0xf bank_mask:0xf
	v_mov_b32_dpp v221, v185 quad_perm:[1,0,3,2] row_mask:0xf bank_mask:0xf
	v_mov_b32_dpp v222, v186 quad_perm:[1,0,3,2] row_mask:0xf bank_mask:0xf
	v_mov_b32_dpp v223, v187 quad_perm:[1,0,3,2] row_mask:0xf bank_mask:0xf
	s_mov_b64 exec, s[62:63]
	v_mov_b32_e32 v168, v220
	v_mov_b32_e32 v169, v221
	v_mov_b32_e32 v170, v222
	v_mov_b32_e32 v171, v223
	s_mov_b64 exec, s[84:85]
	v_mov_b32_e32 v184, v216
	v_mov_b32_e32 v185, v217
	v_mov_b32_e32 v186, v218
	v_mov_b32_e32 v187, v219
	s_mov_b64 exec, -1
	s_add_u32 s80, s10, 0x40000
	s_addc_u32 s81, s11, 0
	s_add_u32 s82, s10, 0x42000
	s_addc_u32 s83, s11, 0
	global_store_dwordx4 v173, v[168:171], s[80:81]
	global_store_dwordx4 v173, v[184:187], s[82:83]
	v_fma_f32 v94, v94, v180, v26
	v_fma_f32 v95, v95, v180, v27
	v_fma_f32 v96, v96, v180, v28
	v_fma_f32 v97, v97, v180, v29
	v_fma_f32 v90, v90, v180, v30
	v_fma_f32 v91, v91, v180, v31
	v_fma_f32 v92, v92, v180, v32
	v_fma_f32 v93, v93, v180, v33
	v_mul_f32_e32 v216, 0x3fb8aa3b, v94
	v_mul_f32_e32 v217, 0x3fb8aa3b, v95
	v_mul_f32_e32 v218, 0x3fb8aa3b, v96
	v_mul_f32_e32 v219, 0x3fb8aa3b, v97
	v_mul_f32_e32 v220, 0x3fb8aa3b, v90
	v_mul_f32_e32 v221, 0x3fb8aa3b, v91
	v_mul_f32_e32 v222, 0x3fb8aa3b, v92
	v_mul_f32_e32 v223, 0x3fb8aa3b, v93
	v_exp_f32_e32 v216, v216
	v_exp_f32_e32 v217, v217
	v_exp_f32_e32 v218, v218
	v_exp_f32_e32 v219, v219
	v_exp_f32_e32 v220, v220
	v_exp_f32_e32 v221, v221
	v_exp_f32_e32 v222, v222
	v_exp_f32_e32 v223, v223
	v_add_f32_e32 v216, 1.0, v216
	v_add_f32_e32 v217, 1.0, v217
	v_add_f32_e32 v218, 1.0, v218
	v_add_f32_e32 v219, 1.0, v219
	v_add_f32_e32 v220, 1.0, v220
	v_add_f32_e32 v221, 1.0, v221
	v_add_f32_e32 v222, 1.0, v222
	v_add_f32_e32 v223, 1.0, v223
	v_rcp_f32_e32 v216, v216
	v_rcp_f32_e32 v217, v217
	v_rcp_f32_e32 v218, v218
	v_rcp_f32_e32 v219, v219
	v_rcp_f32_e32 v220, v220
	v_rcp_f32_e32 v221, v221
	v_rcp_f32_e32 v222, v222
	v_rcp_f32_e32 v223, v223
	v_mul_f32_e32 v216, v216, v224
	v_mul_f32_e32 v217, v217, v225
	v_mul_f32_e32 v218, v218, v226
	v_mul_f32_e32 v219, v219, v227
	v_mul_f32_e32 v220, v220, v228
	v_mul_f32_e32 v221, v221, v229
	v_mul_f32_e32 v222, v222, v230
	v_mul_f32_e32 v223, v223, v231
	v_cvt_pk_f16_f32 v168, v216, v217
	v_cvt_pk_f16_f32 v169, v218, v219
	v_cvt_pk_f16_f32 v170, v220, v221
	v_cvt_pk_f16_f32 v171, v222, v223
	v_fma_f32 v86, v86, v180, v42
	v_fma_f32 v87, v87, v180, v43
	v_fma_f32 v88, v88, v180, v44
	v_fma_f32 v89, v89, v180, v45
	v_fma_f32 v82, v82, v180, v46
	v_fma_f32 v83, v83, v180, v47
	v_fma_f32 v84, v84, v180, v48
	v_fma_f32 v85, v85, v180, v49
	v_mul_f32_e32 v216, 0x3fb8aa3b, v86
	v_mul_f32_e32 v217, 0x3fb8aa3b, v87
	v_mul_f32_e32 v218, 0x3fb8aa3b, v88
	v_mul_f32_e32 v219, 0x3fb8aa3b, v89
	v_mul_f32_e32 v220, 0x3fb8aa3b, v82
	v_mul_f32_e32 v221, 0x3fb8aa3b, v83
	v_mul_f32_e32 v222, 0x3fb8aa3b, v84
	v_mul_f32_e32 v223, 0x3fb8aa3b, v85
	v_exp_f32_e32 v216, v216
	v_exp_f32_e32 v217, v217
	v_exp_f32_e32 v218, v218
	v_exp_f32_e32 v219, v219
	v_exp_f32_e32 v220, v220
	v_exp_f32_e32 v221, v221
	v_exp_f32_e32 v222, v222
	v_exp_f32_e32 v223, v223
	v_add_f32_e32 v216, 1.0, v216
	v_add_f32_e32 v217, 1.0, v217
	v_add_f32_e32 v218, 1.0, v218
	v_add_f32_e32 v219, 1.0, v219
	v_add_f32_e32 v220, 1.0, v220
	v_add_f32_e32 v221, 1.0, v221
	v_add_f32_e32 v222, 1.0, v222
	v_add_f32_e32 v223, 1.0, v223
	v_rcp_f32_e32 v216, v216
	v_rcp_f32_e32 v217, v217
	v_rcp_f32_e32 v218, v218
	v_rcp_f32_e32 v219, v219
	v_rcp_f32_e32 v220, v220
	v_rcp_f32_e32 v221, v221
	v_rcp_f32_e32 v222, v222
	v_rcp_f32_e32 v223, v223
	v_mul_f32_e32 v216, v216, v232
	v_mul_f32_e32 v217, v217, v233
	v_mul_f32_e32 v218, v218, v234
	v_mul_f32_e32 v219, v219, v235
	v_mul_f32_e32 v220, v220, v236
	v_mul_f32_e32 v221, v221, v237
	v_mul_f32_e32 v222, v222, v238
	v_mul_f32_e32 v223, v223, v239
	v_cvt_pk_f16_f32 v184, v216, v217
	v_cvt_pk_f16_f32 v185, v218, v219
	v_cvt_pk_f16_f32 v186, v220, v221
	v_cvt_pk_f16_f32 v187, v222, v223
	v_mov_b32_dpp v216, v168 quad_perm:[1,0,3,2] row_mask:0xf bank_mask:0xf
	v_mov_b32_dpp v217, v169 quad_perm:[1,0,3,2] row_mask:0xf bank_mask:0xf
	v_mov_b32_dpp v218, v170 quad_perm:[1,0,3,2] row_mask:0xf bank_mask:0xf
	v_mov_b32_dpp v219, v171 quad_perm:[1,0,3,2] row_mask:0xf bank_mask:0xf
	v_mov_b32_dpp v220, v184 quad_perm:[1,0,3,2] row_mask:0xf bank_mask:0xf
	v_mov_b32_dpp v221, v185 quad_perm:[1,0,3,2] row_mask:0xf bank_mask:0xf
	v_mov_b32_dpp v222, v186 quad_perm:[1,0,3,2] row_mask:0xf bank_mask:0xf
	v_mov_b32_dpp v223, v187 quad_perm:[1,0,3,2] row_mask:0xf bank_mask:0xf
	s_mov_b64 exec, s[62:63]
	v_mov_b32_e32 v168, v220
	v_mov_b32_e32 v169, v221
	v_mov_b32_e32 v170, v222
	v_mov_b32_e32 v171, v223
	s_mov_b64 exec, s[84:85]
	v_mov_b32_e32 v184, v216
	v_mov_b32_e32 v185, v217
	v_mov_b32_e32 v186, v218
	v_mov_b32_e32 v187, v219
	s_mov_b64 exec, -1
	s_add_u32 s80, s10, 0x60000
	s_addc_u32 s81, s11, 0
	s_add_u32 s82, s10, 0x62000
	s_addc_u32 s83, s11, 0
	global_store_dwordx4 v173, v[168:171], s[80:81]
	global_store_dwordx4 v173, v[184:187], s[82:83]
	v_fma_f32 v78, v78, v181, v26
	v_fma_f32 v79, v79, v181, v27
	v_fma_f32 v80, v80, v181, v28
	v_fma_f32 v81, v81, v181, v29
	v_fma_f32 v74, v74, v181, v30
	v_fma_f32 v75, v75, v181, v31
	v_fma_f32 v76, v76, v181, v32
	v_fma_f32 v77, v77, v181, v33
	v_mul_f32_e32 v216, 0x3fb8aa3b, v78
	v_mul_f32_e32 v217, 0x3fb8aa3b, v79
	v_mul_f32_e32 v218, 0x3fb8aa3b, v80
	v_mul_f32_e32 v219, 0x3fb8aa3b, v81
	v_mul_f32_e32 v220, 0x3fb8aa3b, v74
	v_mul_f32_e32 v221, 0x3fb8aa3b, v75
	v_mul_f32_e32 v222, 0x3fb8aa3b, v76
	v_mul_f32_e32 v223, 0x3fb8aa3b, v77
	v_exp_f32_e32 v216, v216
	v_exp_f32_e32 v217, v217
	v_exp_f32_e32 v218, v218
	v_exp_f32_e32 v219, v219
	v_exp_f32_e32 v220, v220
	v_exp_f32_e32 v221, v221
	v_exp_f32_e32 v222, v222
	v_exp_f32_e32 v223, v223
	v_add_f32_e32 v216, 1.0, v216
	v_add_f32_e32 v217, 1.0, v217
	v_add_f32_e32 v218, 1.0, v218
	v_add_f32_e32 v219, 1.0, v219
	v_add_f32_e32 v220, 1.0, v220
	v_add_f32_e32 v221, 1.0, v221
	v_add_f32_e32 v222, 1.0, v222
	v_add_f32_e32 v223, 1.0, v223
	v_rcp_f32_e32 v216, v216
	v_rcp_f32_e32 v217, v217
	v_rcp_f32_e32 v218, v218
	v_rcp_f32_e32 v219, v219
	v_rcp_f32_e32 v220, v220
	v_rcp_f32_e32 v221, v221
	v_rcp_f32_e32 v222, v222
	v_rcp_f32_e32 v223, v223
	v_mul_f32_e32 v216, v216, v224
	v_mul_f32_e32 v217, v217, v225
	v_mul_f32_e32 v218, v218, v226
	v_mul_f32_e32 v219, v219, v227
	v_mul_f32_e32 v220, v220, v228
	v_mul_f32_e32 v221, v221, v229
	v_mul_f32_e32 v222, v222, v230
	v_mul_f32_e32 v223, v223, v231
	v_cvt_pk_f16_f32 v168, v216, v217
	v_cvt_pk_f16_f32 v169, v218, v219
	v_cvt_pk_f16_f32 v170, v220, v221
	v_cvt_pk_f16_f32 v171, v222, v223
	v_fma_f32 v70, v70, v181, v42
	v_fma_f32 v71, v71, v181, v43
	v_fma_f32 v72, v72, v181, v44
	v_fma_f32 v73, v73, v181, v45
	v_fma_f32 v66, v66, v181, v46
	v_fma_f32 v67, v67, v181, v47
	v_fma_f32 v68, v68, v181, v48
	v_fma_f32 v69, v69, v181, v49
	v_mul_f32_e32 v216, 0x3fb8aa3b, v70
	v_mul_f32_e32 v217, 0x3fb8aa3b, v71
	v_mul_f32_e32 v218, 0x3fb8aa3b, v72
	v_mul_f32_e32 v219, 0x3fb8aa3b, v73
	v_mul_f32_e32 v220, 0x3fb8aa3b, v66
	v_mul_f32_e32 v221, 0x3fb8aa3b, v67
	v_mul_f32_e32 v222, 0x3fb8aa3b, v68
	v_mul_f32_e32 v223, 0x3fb8aa3b, v69
	v_exp_f32_e32 v216, v216
	v_exp_f32_e32 v217, v217
	v_exp_f32_e32 v218, v218
	v_exp_f32_e32 v219, v219
	v_exp_f32_e32 v220, v220
	v_exp_f32_e32 v221, v221
	v_exp_f32_e32 v222, v222
	v_exp_f32_e32 v223, v223
	v_add_f32_e32 v216, 1.0, v216
	v_add_f32_e32 v217, 1.0, v217
	v_add_f32_e32 v218, 1.0, v218
	v_add_f32_e32 v219, 1.0, v219
	v_add_f32_e32 v220, 1.0, v220
	v_add_f32_e32 v221, 1.0, v221
	v_add_f32_e32 v222, 1.0, v222
	v_add_f32_e32 v223, 1.0, v223
	v_rcp_f32_e32 v216, v216
	v_rcp_f32_e32 v217, v217
	v_rcp_f32_e32 v218, v218
	v_rcp_f32_e32 v219, v219
	v_rcp_f32_e32 v220, v220
	v_rcp_f32_e32 v221, v221
	v_rcp_f32_e32 v222, v222
	v_rcp_f32_e32 v223, v223
	v_mul_f32_e32 v216, v216, v232
	v_mul_f32_e32 v217, v217, v233
	v_mul_f32_e32 v218, v218, v234
	v_mul_f32_e32 v219, v219, v235
	v_mul_f32_e32 v220, v220, v236
	v_mul_f32_e32 v221, v221, v237
	v_mul_f32_e32 v222, v222, v238
	v_mul_f32_e32 v223, v223, v239
	v_cvt_pk_f16_f32 v184, v216, v217
	v_cvt_pk_f16_f32 v185, v218, v219
	v_cvt_pk_f16_f32 v186, v220, v221
	v_cvt_pk_f16_f32 v187, v222, v223
	v_mov_b32_dpp v216, v168 quad_perm:[1,0,3,2] row_mask:0xf bank_mask:0xf
	v_mov_b32_dpp v217, v169 quad_perm:[1,0,3,2] row_mask:0xf bank_mask:0xf
	v_mov_b32_dpp v218, v170 quad_perm:[1,0,3,2] row_mask:0xf bank_mask:0xf
	v_mov_b32_dpp v219, v171 quad_perm:[1,0,3,2] row_mask:0xf bank_mask:0xf
	v_mov_b32_dpp v220, v184 quad_perm:[1,0,3,2] row_mask:0xf bank_mask:0xf
	v_mov_b32_dpp v221, v185 quad_perm:[1,0,3,2] row_mask:0xf bank_mask:0xf
	v_mov_b32_dpp v222, v186 quad_perm:[1,0,3,2] row_mask:0xf bank_mask:0xf
	v_mov_b32_dpp v223, v187 quad_perm:[1,0,3,2] row_mask:0xf bank_mask:0xf
	s_mov_b64 exec, s[62:63]
	v_mov_b32_e32 v168, v220
	v_mov_b32_e32 v169, v221
	v_mov_b32_e32 v170, v222
	v_mov_b32_e32 v171, v223
	s_mov_b64 exec, s[84:85]
	v_mov_b32_e32 v184, v216
	v_mov_b32_e32 v185, v217
	v_mov_b32_e32 v186, v218
	v_mov_b32_e32 v187, v219
	s_mov_b64 exec, -1
	s_add_u32 s80, s10, 0x100000
	s_addc_u32 s81, s11, 0
	s_add_u32 s82, s10, 0x102000
	s_addc_u32 s83, s11, 0
	global_store_dwordx4 v173, v[168:171], s[80:81]
	global_store_dwordx4 v173, v[184:187], s[82:83]
	v_fma_f32 v62, v62, v182, v26
	v_fma_f32 v63, v63, v182, v27
	v_fma_f32 v64, v64, v182, v28
	v_fma_f32 v65, v65, v182, v29
	v_fma_f32 v58, v58, v182, v30
	v_fma_f32 v59, v59, v182, v31
	v_fma_f32 v60, v60, v182, v32
	v_fma_f32 v61, v61, v182, v33
	v_mul_f32_e32 v216, 0x3fb8aa3b, v62
	v_mul_f32_e32 v217, 0x3fb8aa3b, v63
	v_mul_f32_e32 v218, 0x3fb8aa3b, v64
	v_mul_f32_e32 v219, 0x3fb8aa3b, v65
	v_mul_f32_e32 v220, 0x3fb8aa3b, v58
	v_mul_f32_e32 v221, 0x3fb8aa3b, v59
	v_mul_f32_e32 v222, 0x3fb8aa3b, v60
	v_mul_f32_e32 v223, 0x3fb8aa3b, v61
	v_exp_f32_e32 v216, v216
	v_exp_f32_e32 v217, v217
	v_exp_f32_e32 v218, v218
	v_exp_f32_e32 v219, v219
	v_exp_f32_e32 v220, v220
	v_exp_f32_e32 v221, v221
	v_exp_f32_e32 v222, v222
	v_exp_f32_e32 v223, v223
	v_add_f32_e32 v216, 1.0, v216
	v_add_f32_e32 v217, 1.0, v217
	v_add_f32_e32 v218, 1.0, v218
	v_add_f32_e32 v219, 1.0, v219
	v_add_f32_e32 v220, 1.0, v220
	v_add_f32_e32 v221, 1.0, v221
	v_add_f32_e32 v222, 1.0, v222
	v_add_f32_e32 v223, 1.0, v223
	v_rcp_f32_e32 v216, v216
	v_rcp_f32_e32 v217, v217
	v_rcp_f32_e32 v218, v218
	v_rcp_f32_e32 v219, v219
	v_rcp_f32_e32 v220, v220
	v_rcp_f32_e32 v221, v221
	v_rcp_f32_e32 v222, v222
	v_rcp_f32_e32 v223, v223
	v_mul_f32_e32 v216, v216, v224
	v_mul_f32_e32 v217, v217, v225
	v_mul_f32_e32 v218, v218, v226
	v_mul_f32_e32 v219, v219, v227
	v_mul_f32_e32 v220, v220, v228
	v_mul_f32_e32 v221, v221, v229
	v_mul_f32_e32 v222, v222, v230
	v_mul_f32_e32 v223, v223, v231
	v_cvt_pk_f16_f32 v168, v216, v217
	v_cvt_pk_f16_f32 v169, v218, v219
	v_cvt_pk_f16_f32 v170, v220, v221
	v_cvt_pk_f16_f32 v171, v222, v223
	v_fma_f32 v54, v54, v182, v42
	v_fma_f32 v55, v55, v182, v43
	v_fma_f32 v56, v56, v182, v44
	v_fma_f32 v57, v57, v182, v45
	v_fma_f32 v50, v50, v182, v46
	v_fma_f32 v51, v51, v182, v47
	v_fma_f32 v52, v52, v182, v48
	v_fma_f32 v53, v53, v182, v49
	v_mul_f32_e32 v216, 0x3fb8aa3b, v54
	v_mul_f32_e32 v217, 0x3fb8aa3b, v55
	v_mul_f32_e32 v218, 0x3fb8aa3b, v56
	v_mul_f32_e32 v219, 0x3fb8aa3b, v57
	v_mul_f32_e32 v220, 0x3fb8aa3b, v50
	v_mul_f32_e32 v221, 0x3fb8aa3b, v51
	v_mul_f32_e32 v222, 0x3fb8aa3b, v52
	v_mul_f32_e32 v223, 0x3fb8aa3b, v53
	v_exp_f32_e32 v216, v216
	v_exp_f32_e32 v217, v217
	v_exp_f32_e32 v218, v218
	v_exp_f32_e32 v219, v219
	v_exp_f32_e32 v220, v220
	v_exp_f32_e32 v221, v221
	v_exp_f32_e32 v222, v222
	v_exp_f32_e32 v223, v223
	v_add_f32_e32 v216, 1.0, v216
	v_add_f32_e32 v217, 1.0, v217
	v_add_f32_e32 v218, 1.0, v218
	v_add_f32_e32 v219, 1.0, v219
	v_add_f32_e32 v220, 1.0, v220
	v_add_f32_e32 v221, 1.0, v221
	v_add_f32_e32 v222, 1.0, v222
	v_add_f32_e32 v223, 1.0, v223
	v_rcp_f32_e32 v216, v216
	v_rcp_f32_e32 v217, v217
	v_rcp_f32_e32 v218, v218
	v_rcp_f32_e32 v219, v219
	v_rcp_f32_e32 v220, v220
	v_rcp_f32_e32 v221, v221
	v_rcp_f32_e32 v222, v222
	v_rcp_f32_e32 v223, v223
	v_mul_f32_e32 v216, v216, v232
	v_mul_f32_e32 v217, v217, v233
	v_mul_f32_e32 v218, v218, v234
	v_mul_f32_e32 v219, v219, v235
	v_mul_f32_e32 v220, v220, v236
	v_mul_f32_e32 v221, v221, v237
	v_mul_f32_e32 v222, v222, v238
	v_mul_f32_e32 v223, v223, v239
	v_cvt_pk_f16_f32 v184, v216, v217
	v_cvt_pk_f16_f32 v185, v218, v219
	v_cvt_pk_f16_f32 v186, v220, v221
	v_cvt_pk_f16_f32 v187, v222, v223
	v_mov_b32_dpp v216, v168 quad_perm:[1,0,3,2] row_mask:0xf bank_mask:0xf
	v_mov_b32_dpp v217, v169 quad_perm:[1,0,3,2] row_mask:0xf bank_mask:0xf
	v_mov_b32_dpp v218, v170 quad_perm:[1,0,3,2] row_mask:0xf bank_mask:0xf
	v_mov_b32_dpp v219, v171 quad_perm:[1,0,3,2] row_mask:0xf bank_mask:0xf
	v_mov_b32_dpp v220, v184 quad_perm:[1,0,3,2] row_mask:0xf bank_mask:0xf
	v_mov_b32_dpp v221, v185 quad_perm:[1,0,3,2] row_mask:0xf bank_mask:0xf
	v_mov_b32_dpp v222, v186 quad_perm:[1,0,3,2] row_mask:0xf bank_mask:0xf
	v_mov_b32_dpp v223, v187 quad_perm:[1,0,3,2] row_mask:0xf bank_mask:0xf
	s_mov_b64 exec, s[62:63]
	v_mov_b32_e32 v168, v220
	v_mov_b32_e32 v169, v221
	v_mov_b32_e32 v170, v222
	v_mov_b32_e32 v171, v223
	s_mov_b64 exec, s[84:85]
	v_mov_b32_e32 v184, v216
	v_mov_b32_e32 v185, v217
	v_mov_b32_e32 v186, v218
	v_mov_b32_e32 v187, v219
	s_mov_b64 exec, -1
	s_add_u32 s80, s10, 0x120000
	s_addc_u32 s81, s11, 0
	s_add_u32 s82, s10, 0x122000
	s_addc_u32 s83, s11, 0
	global_store_dwordx4 v173, v[168:171], s[80:81]
	global_store_dwordx4 v173, v[184:187], s[82:83]
	v_fma_f32 v38, v38, v188, v26
	v_fma_f32 v39, v39, v188, v27
	v_fma_f32 v40, v40, v188, v28
	v_fma_f32 v41, v41, v188, v29
	v_fma_f32 v34, v34, v188, v30
	v_fma_f32 v35, v35, v188, v31
	v_fma_f32 v36, v36, v188, v32
	v_fma_f32 v37, v37, v188, v33
	v_mul_f32_e32 v216, 0x3fb8aa3b, v38
	v_mul_f32_e32 v217, 0x3fb8aa3b, v39
	v_mul_f32_e32 v218, 0x3fb8aa3b, v40
	v_mul_f32_e32 v219, 0x3fb8aa3b, v41
	v_mul_f32_e32 v220, 0x3fb8aa3b, v34
	v_mul_f32_e32 v221, 0x3fb8aa3b, v35
	v_mul_f32_e32 v222, 0x3fb8aa3b, v36
	v_mul_f32_e32 v223, 0x3fb8aa3b, v37
	v_exp_f32_e32 v216, v216
	v_exp_f32_e32 v217, v217
	v_exp_f32_e32 v218, v218
	v_exp_f32_e32 v219, v219
	v_exp_f32_e32 v220, v220
	v_exp_f32_e32 v221, v221
	v_exp_f32_e32 v222, v222
	v_exp_f32_e32 v223, v223
	v_add_f32_e32 v216, 1.0, v216
	v_add_f32_e32 v217, 1.0, v217
	v_add_f32_e32 v218, 1.0, v218
	v_add_f32_e32 v219, 1.0, v219
	v_add_f32_e32 v220, 1.0, v220
	v_add_f32_e32 v221, 1.0, v221
	v_add_f32_e32 v222, 1.0, v222
	v_add_f32_e32 v223, 1.0, v223
	v_rcp_f32_e32 v216, v216
	v_rcp_f32_e32 v217, v217
	v_rcp_f32_e32 v218, v218
	v_rcp_f32_e32 v219, v219
	v_rcp_f32_e32 v220, v220
	v_rcp_f32_e32 v221, v221
	v_rcp_f32_e32 v222, v222
	v_rcp_f32_e32 v223, v223
	v_mul_f32_e32 v216, v216, v224
	v_mul_f32_e32 v217, v217, v225
	v_mul_f32_e32 v218, v218, v226
	v_mul_f32_e32 v219, v219, v227
	v_mul_f32_e32 v220, v220, v228
	v_mul_f32_e32 v221, v221, v229
	v_mul_f32_e32 v222, v222, v230
	v_mul_f32_e32 v223, v223, v231
	v_cvt_pk_f16_f32 v168, v216, v217
	v_cvt_pk_f16_f32 v169, v218, v219
	v_cvt_pk_f16_f32 v170, v220, v221
	v_cvt_pk_f16_f32 v171, v222, v223
	v_fma_f32 v22, v22, v188, v42
	v_fma_f32 v23, v23, v188, v43
	v_fma_f32 v24, v24, v188, v44
	v_fma_f32 v25, v25, v188, v45
	v_fma_f32 v18, v18, v188, v46
	v_fma_f32 v19, v19, v188, v47
	v_fma_f32 v20, v20, v188, v48
	v_fma_f32 v21, v21, v188, v49
	v_mul_f32_e32 v216, 0x3fb8aa3b, v22
	v_mul_f32_e32 v217, 0x3fb8aa3b, v23
	v_mul_f32_e32 v218, 0x3fb8aa3b, v24
	v_mul_f32_e32 v219, 0x3fb8aa3b, v25
	v_mul_f32_e32 v220, 0x3fb8aa3b, v18
	v_mul_f32_e32 v221, 0x3fb8aa3b, v19
	v_mul_f32_e32 v222, 0x3fb8aa3b, v20
	v_mul_f32_e32 v223, 0x3fb8aa3b, v21
	v_exp_f32_e32 v216, v216
	v_exp_f32_e32 v217, v217
	v_exp_f32_e32 v218, v218
	v_exp_f32_e32 v219, v219
	v_exp_f32_e32 v220, v220
	v_exp_f32_e32 v221, v221
	v_exp_f32_e32 v222, v222
	v_exp_f32_e32 v223, v223
	v_add_f32_e32 v216, 1.0, v216
	v_add_f32_e32 v217, 1.0, v217
	v_add_f32_e32 v218, 1.0, v218
	v_add_f32_e32 v219, 1.0, v219
	v_add_f32_e32 v220, 1.0, v220
	v_add_f32_e32 v221, 1.0, v221
	v_add_f32_e32 v222, 1.0, v222
	v_add_f32_e32 v223, 1.0, v223
	v_rcp_f32_e32 v216, v216
	v_rcp_f32_e32 v217, v217
	v_rcp_f32_e32 v218, v218
	v_rcp_f32_e32 v219, v219
	v_rcp_f32_e32 v220, v220
	v_rcp_f32_e32 v221, v221
	v_rcp_f32_e32 v222, v222
	v_rcp_f32_e32 v223, v223
	v_mul_f32_e32 v216, v216, v232
	v_mul_f32_e32 v217, v217, v233
	v_mul_f32_e32 v218, v218, v234
	v_mul_f32_e32 v219, v219, v235
	v_mul_f32_e32 v220, v220, v236
	v_mul_f32_e32 v221, v221, v237
	v_mul_f32_e32 v222, v222, v238
	v_mul_f32_e32 v223, v223, v239
	v_cvt_pk_f16_f32 v184, v216, v217
	v_cvt_pk_f16_f32 v185, v218, v219
	v_cvt_pk_f16_f32 v186, v220, v221
	v_cvt_pk_f16_f32 v187, v222, v223
	v_mov_b32_dpp v216, v168 quad_perm:[1,0,3,2] row_mask:0xf bank_mask:0xf
	v_mov_b32_dpp v217, v169 quad_perm:[1,0,3,2] row_mask:0xf bank_mask:0xf
	v_mov_b32_dpp v218, v170 quad_perm:[1,0,3,2] row_mask:0xf bank_mask:0xf
	v_mov_b32_dpp v219, v171 quad_perm:[1,0,3,2] row_mask:0xf bank_mask:0xf
	v_mov_b32_dpp v220, v184 quad_perm:[1,0,3,2] row_mask:0xf bank_mask:0xf
	v_mov_b32_dpp v221, v185 quad_perm:[1,0,3,2] row_mask:0xf bank_mask:0xf
	v_mov_b32_dpp v222, v186 quad_perm:[1,0,3,2] row_mask:0xf bank_mask:0xf
	v_mov_b32_dpp v223, v187 quad_perm:[1,0,3,2] row_mask:0xf bank_mask:0xf
	s_mov_b64 exec, s[62:63]
	v_mov_b32_e32 v168, v220
	v_mov_b32_e32 v169, v221
	v_mov_b32_e32 v170, v222
	v_mov_b32_e32 v171, v223
	s_mov_b64 exec, s[84:85]
	v_mov_b32_e32 v184, v216
	v_mov_b32_e32 v185, v217
	v_mov_b32_e32 v186, v218
	v_mov_b32_e32 v187, v219
	s_mov_b64 exec, -1
	s_add_u32 s80, s10, 0x140000
	s_addc_u32 s81, s11, 0
	s_add_u32 s82, s10, 0x142000
	s_addc_u32 s83, s11, 0
	global_store_dwordx4 v173, v[168:171], s[80:81]
	global_store_dwordx4 v173, v[184:187], s[82:83]
	v_fma_f32 v14, v14, v189, v26
	v_fma_f32 v15, v15, v189, v27
	v_fma_f32 v16, v16, v189, v28
	v_fma_f32 v17, v17, v189, v29
	v_fma_f32 v10, v10, v189, v30
	v_fma_f32 v11, v11, v189, v31
	v_fma_f32 v12, v12, v189, v32
	v_fma_f32 v13, v13, v189, v33
	v_mul_f32_e32 v216, 0x3fb8aa3b, v14
	v_mul_f32_e32 v217, 0x3fb8aa3b, v15
	v_mul_f32_e32 v218, 0x3fb8aa3b, v16
	v_mul_f32_e32 v219, 0x3fb8aa3b, v17
	v_mul_f32_e32 v220, 0x3fb8aa3b, v10
	v_mul_f32_e32 v221, 0x3fb8aa3b, v11
	v_mul_f32_e32 v222, 0x3fb8aa3b, v12
	v_mul_f32_e32 v223, 0x3fb8aa3b, v13
	v_exp_f32_e32 v216, v216
	v_exp_f32_e32 v217, v217
	v_exp_f32_e32 v218, v218
	v_exp_f32_e32 v219, v219
	v_exp_f32_e32 v220, v220
	v_exp_f32_e32 v221, v221
	v_exp_f32_e32 v222, v222
	v_exp_f32_e32 v223, v223
	v_add_f32_e32 v216, 1.0, v216
	v_add_f32_e32 v217, 1.0, v217
	v_add_f32_e32 v218, 1.0, v218
	v_add_f32_e32 v219, 1.0, v219
	v_add_f32_e32 v220, 1.0, v220
	v_add_f32_e32 v221, 1.0, v221
	v_add_f32_e32 v222, 1.0, v222
	v_add_f32_e32 v223, 1.0, v223
	v_rcp_f32_e32 v216, v216
	v_rcp_f32_e32 v217, v217
	v_rcp_f32_e32 v218, v218
	v_rcp_f32_e32 v219, v219
	v_rcp_f32_e32 v220, v220
	v_rcp_f32_e32 v221, v221
	v_rcp_f32_e32 v222, v222
	v_rcp_f32_e32 v223, v223
	v_mul_f32_e32 v216, v216, v224
	v_mul_f32_e32 v217, v217, v225
	v_mul_f32_e32 v218, v218, v226
	v_mul_f32_e32 v219, v219, v227
	v_mul_f32_e32 v220, v220, v228
	v_mul_f32_e32 v221, v221, v229
	v_mul_f32_e32 v222, v222, v230
	v_mul_f32_e32 v223, v223, v231
	v_cvt_pk_f16_f32 v168, v216, v217
	v_cvt_pk_f16_f32 v169, v218, v219
	v_cvt_pk_f16_f32 v170, v220, v221
	v_cvt_pk_f16_f32 v171, v222, v223
	v_fma_f32 v6, v6, v189, v42
	v_fma_f32 v7, v7, v189, v43
	v_fma_f32 v8, v8, v189, v44
	v_fma_f32 v9, v9, v189, v45
	v_fma_f32 v2, v2, v189, v46
	v_fma_f32 v3, v3, v189, v47
	v_fma_f32 v4, v4, v189, v48
	v_fma_f32 v5, v5, v189, v49
	v_mul_f32_e32 v216, 0x3fb8aa3b, v6
	v_mul_f32_e32 v217, 0x3fb8aa3b, v7
	v_mul_f32_e32 v218, 0x3fb8aa3b, v8
	v_mul_f32_e32 v219, 0x3fb8aa3b, v9
	v_mul_f32_e32 v220, 0x3fb8aa3b, v2
	v_mul_f32_e32 v221, 0x3fb8aa3b, v3
	v_mul_f32_e32 v222, 0x3fb8aa3b, v4
	v_mul_f32_e32 v223, 0x3fb8aa3b, v5
	v_exp_f32_e32 v216, v216
	v_exp_f32_e32 v217, v217
	v_exp_f32_e32 v218, v218
	v_exp_f32_e32 v219, v219
	v_exp_f32_e32 v220, v220
	v_exp_f32_e32 v221, v221
	v_exp_f32_e32 v222, v222
	v_exp_f32_e32 v223, v223
	v_add_f32_e32 v216, 1.0, v216
	v_add_f32_e32 v217, 1.0, v217
	v_add_f32_e32 v218, 1.0, v218
	v_add_f32_e32 v219, 1.0, v219
	v_add_f32_e32 v220, 1.0, v220
	v_add_f32_e32 v221, 1.0, v221
	v_add_f32_e32 v222, 1.0, v222
	v_add_f32_e32 v223, 1.0, v223
	v_rcp_f32_e32 v216, v216
	v_rcp_f32_e32 v217, v217
	v_rcp_f32_e32 v218, v218
	v_rcp_f32_e32 v219, v219
	v_rcp_f32_e32 v220, v220
	v_rcp_f32_e32 v221, v221
	v_rcp_f32_e32 v222, v222
	v_rcp_f32_e32 v223, v223
	v_mul_f32_e32 v216, v216, v232
	v_mul_f32_e32 v217, v217, v233
	v_mul_f32_e32 v218, v218, v234
	v_mul_f32_e32 v219, v219, v235
	v_mul_f32_e32 v220, v220, v236
	v_mul_f32_e32 v221, v221, v237
	v_mul_f32_e32 v222, v222, v238
	v_mul_f32_e32 v223, v223, v239
	v_cvt_pk_f16_f32 v184, v216, v217
	v_cvt_pk_f16_f32 v185, v218, v219
	v_cvt_pk_f16_f32 v186, v220, v221
	v_cvt_pk_f16_f32 v187, v222, v223
	v_mov_b32_dpp v216, v168 quad_perm:[1,0,3,2] row_mask:0xf bank_mask:0xf
	v_mov_b32_dpp v217, v169 quad_perm:[1,0,3,2] row_mask:0xf bank_mask:0xf
	v_mov_b32_dpp v218, v170 quad_perm:[1,0,3,2] row_mask:0xf bank_mask:0xf
	v_mov_b32_dpp v219, v171 quad_perm:[1,0,3,2] row_mask:0xf bank_mask:0xf
	v_mov_b32_dpp v220, v184 quad_perm:[1,0,3,2] row_mask:0xf bank_mask:0xf
	v_mov_b32_dpp v221, v185 quad_perm:[1,0,3,2] row_mask:0xf bank_mask:0xf
	v_mov_b32_dpp v222, v186 quad_perm:[1,0,3,2] row_mask:0xf bank_mask:0xf
	v_mov_b32_dpp v223, v187 quad_perm:[1,0,3,2] row_mask:0xf bank_mask:0xf
	s_mov_b64 exec, s[62:63]
	v_mov_b32_e32 v168, v220
	v_mov_b32_e32 v169, v221
	v_mov_b32_e32 v170, v222
	v_mov_b32_e32 v171, v223
	s_mov_b64 exec, s[84:85]
	v_mov_b32_e32 v184, v216
	v_mov_b32_e32 v185, v217
	v_mov_b32_e32 v186, v218
	v_mov_b32_e32 v187, v219
	s_mov_b64 exec, -1
	s_add_u32 s80, s10, 0x160000
	s_addc_u32 s81, s11, 0
	s_add_u32 s82, s10, 0x162000
	s_addc_u32 s83, s11, 0
	global_store_dwordx4 v173, v[168:171], s[80:81]
	global_store_dwordx4 v173, v[184:187], s[82:83]
.Lact1_hgin_done:
	s_mov_b64 s[30:31], -1
	s_andn2_b64 vcc, exec, s[14:15]
	s_mov_b64 s[0:1], -1
	s_cbranch_vccnz .LBB0_263
